# scan loops: loop-invariant LDS base adds folded into ds_read 16-bit offsets (27 VALU ops removed from the four chunk-scan loops)
# speedup vs baseline: 1.0017x; 1.0017x over previous
.LBB0_854:
	s_or_b64 exec, exec, s[96:97]
	s_min_i32 s16, s77, s3
	s_lshl_b32 s16, s16, 5
	v_or_b32_e32 v0, s16, v191
	v_xad_u32 v1, v0, -1, s74
	v_cndmask_b32_e64 v0, v1, v0, s[4:5]
	v_add_u32_e32 v1, s16, v192
	v_xad_u32 v3, v1, -1, s74
	v_add_u32_e32 v0, s73, v0
	v_cndmask_b32_e64 v3, v3, v1, s[4:5]
	v_ashrrev_i32_e32 v1, 31, v0
	s_waitcnt vmcnt(7)
	ds_write_b128 v197, v[4:7] offset:61952
	v_mad_i64_i32 v[4:5], s[16:17], v0, s89, v[180:181]
	v_lshlrev_b64 v[0:1], 11, v[0:1]
	v_lshl_add_u64 v[0:1], v[182:183], 0, v[0:1]
	global_load_dwordx4 v[12:15], v[4:5], off
	global_load_dwordx4 v[20:23], v[0:1], off
	v_add_u32_e32 v0, s73, v3
	v_mad_i64_i32 v[0:1], s[16:17], v0, s89, v[184:185]
	global_load_dwordx4 v[4:7], v[0:1], off
	s_waitcnt lgkmcnt(0)
	s_barrier
	ds_read_b64_tr_b16 v[92:93], v204
	ds_read_b64_tr_b16 v[94:95], v204 offset:4352
	ds_read_b64 v[88:89], v205 offset:35840
	ds_read_b64 v[90:91], v205 offset:35872
	ds_read_b64 v[80:81], v205 offset:35904
	ds_read_b64 v[82:83], v205 offset:35936
	ds_read_b64 v[72:73], v205 offset:35968
	ds_read_b64 v[74:75], v205 offset:36000
	ds_read_b64 v[60:61], v205 offset:36032
	ds_read_b64 v[62:63], v205 offset:36064
	ds_read_b64 v[84:85], v205 offset:40192
	ds_read_b64 v[86:87], v205 offset:40224
	ds_read_b64 v[76:77], v205 offset:40256
	ds_read_b64 v[78:79], v205 offset:40288
	ds_read_b64 v[68:69], v205 offset:40320
	ds_read_b64 v[70:71], v205 offset:40352
	ds_read_b64 v[64:65], v205 offset:40384
	ds_read_b64 v[66:67], v205 offset:40416
	ds_read_b64 v[100:101], v201 offset:48896
	ds_read_b64 v[102:103], v201 offset:48928
	ds_read_b64 v[96:97], v201 offset:44544
	ds_read_b64 v[98:99], v201 offset:44576
	ds_read_b64 v[108:109], v201 offset:44608
	ds_read_b64 v[110:111], v201 offset:44640
	ds_read_b64 v[112:113], v201 offset:48960
	ds_read_b64 v[114:115], v201 offset:48992
	s_waitcnt lgkmcnt(6)
	v_mfma_f32_16x16x32_bf16 v[100:103], v[100:103], v[84:87], 0
	s_add_i32 s77, s77, 2
	v_subrev_u32_e32 v222, 64, v222
	s_cmp_ge_u32 s78, s35
	s_waitcnt lgkmcnt(4)
	v_mfma_f32_16x16x32_bf16 v[104:107], v[96:99], v[88:91], 0
	s_waitcnt lgkmcnt(0)
	v_mfma_f32_16x16x32_bf16 v[100:103], v[112:115], v[76:79], v[100:103]
	ds_read_b64 v[112:113], v201 offset:44672
	ds_read_b64 v[114:115], v201 offset:44704
	ds_read_b64 v[116:117], v201 offset:49024
	ds_read_b64 v[118:119], v201 offset:49056
	v_mfma_f32_16x16x32_bf16 v[104:107], v[108:111], v[80:83], v[104:107]
	s_waitcnt lgkmcnt(0)
	v_mfma_f32_16x16x32_bf16 v[100:103], v[116:119], v[68:71], v[100:103]
	ds_read_b64 v[116:117], v201 offset:44736
	ds_read_b64 v[118:119], v201 offset:44768
	ds_read_b64 v[226:227], v201 offset:49088
	ds_read_b64 v[228:229], v201 offset:49120
	v_mov_b32_e32 v0, s93
	v_mfma_f32_16x16x32_bf16 v[96:99], v[96:99], v[84:87], 0
	v_mfma_f32_16x16x32_bf16 v[104:107], v[112:115], v[72:75], v[104:107]
	v_mfma_f32_16x16x32_bf16 v[96:99], v[108:111], v[76:79], v[96:99]
	s_waitcnt lgkmcnt(2)
	v_mfma_f32_16x16x32_bf16 v[104:107], v[116:119], v[60:63], v[104:107]
	s_waitcnt lgkmcnt(0)
	v_mfma_f32_16x16x32_bf16 v[100:103], v[226:229], v[64:67], v[100:103]
	v_mov_b32_e32 v226, s93
	s_nop 4
	v_cndmask_b32_e64 v0, v104, v0, s[8:9]
	v_cndmask_b32_e64 v0, v0, v104, s[10:11]
	v_mfma_f32_16x16x32_bf16 v[96:99], v[112:115], v[68:71], v[96:99]
	v_cndmask_b32_e64 v3, v106, 0, s[12:13]
	v_cndmask_b32_e64 v1, v100, v226, s[8:9]
	v_cndmask_b32_e64 v100, v1, v100, s[10:11]
	v_cndmask_b32_e64 v1, 0, v105, s[10:11]
	v_cndmask_b32_e64 v104, v107, 0, s[14:15]
	v_cvt_pk_bf16_f32 v0, v0, v1
	v_cvt_pk_bf16_f32 v1, v3, v104
	ds_read_b128 v[104:107], v206
	ds_read_b128 v[108:111], v207
	v_mfma_f32_16x16x32_bf16 v[96:99], v[116:119], v[64:67], v[96:99]
	v_cndmask_b32_e64 v101, 0, v101, s[10:11]
	v_cndmask_b32_e64 v102, v102, 0, s[12:13]
	v_cndmask_b32_e64 v103, v103, 0, s[14:15]
	v_mov_b32_e32 v3, v2
	s_waitcnt lgkmcnt(0)
	v_pk_mul_f32 v[110:111], v[54:55], v[110:111]
	s_nop 1
	v_cvt_pk_bf16_f32 v96, v96, v97
	v_cvt_pk_bf16_f32 v97, v98, v99
	v_cvt_pk_bf16_f32 v98, v100, v101
	v_cvt_pk_bf16_f32 v99, v102, v103
	v_mfma_f32_16x16x32_bf16 v[100:103], v[92:95], v[0:3], 0
	v_mul_f32_e64 v0, v58, v106
	v_mul_f32_e64 v1, v59, v107
	v_pk_mul_f32 v[106:107], v[52:53], v[108:109]
	v_pk_mul_f32 v[104:105], v[56:57], v[104:105]
	v_cvt_pk_bf16_f32 v106, v106, v107
	v_cvt_pk_bf16_f32 v107, v110, v111
	ds_read_b128 v[108:111], v208
	ds_read_b128 v[112:115], v209
	v_cvt_pk_bf16_f32 v104, v104, v105
	v_cvt_pk_bf16_f32 v105, v0, v1
	v_mfma_f32_16x16x32_bf16 v[96:99], v[92:95], v[96:99], 0
	s_waitcnt lgkmcnt(1)
	v_pk_mul_f32 v[0:1], v[50:51], v[110:111]
	v_pk_mul_f32 v[108:109], v[48:49], v[108:109]
	s_waitcnt lgkmcnt(0)
	v_pk_mul_f32 v[110:111], v[46:47], v[114:115]
	v_pk_mul_f32 v[112:113], v[44:45], v[112:113]
	v_cvt_pk_bf16_f32 v116, v108, v109
	v_cvt_pk_bf16_f32 v118, v112, v113
	v_cvt_pk_bf16_f32 v119, v110, v111
	ds_read_b128 v[108:111], v210
	ds_read_b128 v[112:115], v211
	v_cvt_pk_bf16_f32 v117, v0, v1
	v_mfma_f32_16x16x32_bf16 v[88:91], v[104:107], v[88:91], v[100:103]
	v_xor_b32_e32 v3, 0xffffffdf, v190
	s_waitcnt lgkmcnt(1)
	v_pk_mul_f32 v[0:1], v[42:43], v[110:111]
	s_waitcnt lgkmcnt(0)
	v_pk_mul_f32 v[114:115], v[38:39], v[114:115]
	v_pk_mul_f32 v[110:111], v[36:37], v[112:113]
	v_pk_mul_f32 v[108:109], v[40:41], v[108:109]
	v_cvt_pk_bf16_f32 v110, v110, v111
	v_cvt_pk_bf16_f32 v111, v114, v115
	ds_read_b128 v[112:115], v212
	ds_read_b128 v[226:229], v213
	v_cvt_pk_bf16_f32 v108, v108, v109
	v_cvt_pk_bf16_f32 v109, v0, v1
	v_mfma_f32_16x16x32_bf16 v[84:87], v[104:107], v[84:87], v[96:99]
	s_waitcnt lgkmcnt(1)
	v_pk_mul_f32 v[0:1], v[34:35], v[114:115]
	s_waitcnt lgkmcnt(0)
	v_pk_mul_f32 v[228:229], v[30:31], v[228:229]
	v_pk_mul_f32 v[114:115], v[28:29], v[226:227]
	v_mfma_f32_16x16x32_bf16 v[80:83], v[116:119], v[80:83], v[88:91]
	v_cvt_pk_bf16_f32 v114, v114, v115
	v_cvt_pk_bf16_f32 v115, v228, v229
	ds_read_b128 v[226:229], v214
	ds_read_b64_tr_b16 v[232:233], v198 offset:57600
	ds_read_b64_tr_b16 v[230:231], v198 offset:53248
	ds_read_b64_tr_b16 v[234:235], v198 offset:53280
	v_pk_mul_f32 v[112:113], v[32:33], v[112:113]
	s_waitcnt lgkmcnt(3)
	v_pk_mul_f32 v[58:59], v[58:59], v[228:229]
	v_pk_mul_f32 v[56:57], v[56:57], v[226:227]
	ds_read_b128 v[226:229], v215
	ds_read_b64_tr_b16 v[236:237], v198 offset:57632
	s_waitcnt lgkmcnt(3)
	v_mfma_f32_16x16x32_bf16 v[56:59], v[230:233], v[92:95], v[56:59]
	v_cvt_pk_bf16_f32 v112, v112, v113
	v_cvt_pk_bf16_f32 v113, v0, v1
	s_waitcnt lgkmcnt(1)
	v_pk_mul_f32 v[54:55], v[54:55], v[228:229]
	v_pk_mul_f32 v[52:53], v[52:53], v[226:227]
	ds_read_b128 v[226:229], v216
	ds_read_b64_tr_b16 v[230:231], v198 offset:53312
	ds_read_b64_tr_b16 v[232:233], v198 offset:57664
	v_mfma_f32_16x16x32_bf16 v[76:79], v[116:119], v[76:79], v[84:87]
	v_add_u32_e32 v0, 32, v190
	s_waitcnt lgkmcnt(2)
	v_pk_mul_f32 v[50:51], v[50:51], v[228:229]
	v_pk_mul_f32 v[48:49], v[48:49], v[226:227]
	v_mfma_f32_16x16x32_bf16 v[72:75], v[108:111], v[72:75], v[80:83]
	v_add_u32_e32 v3, s74, v3
	v_cndmask_b32_e64 v3, v3, v0, s[4:5]
	v_xor_b32_e32 v0, 0xffffffcf, v190
	s_waitcnt lgkmcnt(0)
	v_mfma_f32_16x16x32_bf16 v[48:51], v[230:233], v[92:95], v[48:51]
	ds_read_b128 v[226:229], v217
	ds_read_b64_tr_b16 v[230:231], v198 offset:53344
	ds_read_b64_tr_b16 v[232:233], v198 offset:57696
	v_add_u32_e32 v1, 48, v190
	v_add_u32_e32 v0, s74, v0
	s_waitcnt lgkmcnt(2)
	v_pk_mul_f32 v[46:47], v[46:47], v[228:229]
	v_pk_mul_f32 v[44:45], v[44:45], v[226:227]
	v_mfma_f32_16x16x32_bf16 v[68:71], v[108:111], v[68:71], v[76:79]
	v_add_u32_e32 v190, 64, v190
	s_waitcnt lgkmcnt(0)
	v_mfma_f32_16x16x32_bf16 v[44:47], v[230:233], v[92:95], v[44:47]
	ds_read_b128 v[226:229], v218
	ds_read_b64_tr_b16 v[230:231], v198 offset:53376
	ds_read_b64_tr_b16 v[232:233], v198 offset:57728
	s_waitcnt lgkmcnt(2)
	v_pk_mul_f32 v[42:43], v[42:43], v[228:229]
	v_pk_mul_f32 v[40:41], v[40:41], v[226:227]
	v_mfma_f32_16x16x32_bf16 v[60:63], v[112:115], v[60:63], v[72:75]
	s_waitcnt lgkmcnt(0)
	v_mfma_f32_16x16x32_bf16 v[40:43], v[230:233], v[92:95], v[40:43]
	ds_read_b128 v[226:229], v219
	ds_read_b64_tr_b16 v[230:231], v198 offset:53408
	ds_read_b64_tr_b16 v[232:233], v198 offset:57760
	s_waitcnt lgkmcnt(2)
	v_pk_mul_f32 v[38:39], v[38:39], v[228:229]
	v_pk_mul_f32 v[36:37], v[36:37], v[226:227]
	v_mfma_f32_16x16x32_bf16 v[64:67], v[112:115], v[64:67], v[68:71]
	s_waitcnt lgkmcnt(0)
	v_mfma_f32_16x16x32_bf16 v[36:39], v[230:233], v[92:95], v[36:39]
	ds_read_b128 v[226:229], v220
	ds_read_b64_tr_b16 v[230:231], v198 offset:53440
	ds_read_b64_tr_b16 v[232:233], v198 offset:57792
	v_cndmask_b32_e64 v68, v0, v1, s[4:5]
	v_cvt_pk_bf16_f32 v1, v62, v63
	s_waitcnt lgkmcnt(2)
	v_pk_mul_f32 v[34:35], v[34:35], v[228:229]
	v_pk_mul_f32 v[32:33], v[32:33], v[226:227]
	v_add_u32_e32 v62, s73, v3
	v_ashrrev_i32_e32 v63, 31, v62
	s_waitcnt lgkmcnt(0)
	v_mfma_f32_16x16x32_bf16 v[32:35], v[230:233], v[92:95], v[32:35]
	ds_read_b128 v[226:229], v221
	ds_read_b64_tr_b16 v[230:231], v198 offset:53472
	ds_read_b64_tr_b16 v[232:233], v198 offset:57824
	v_lshlrev_b64 v[62:63], 11, v[62:63]
	v_cvt_pk_bf16_f32 v0, v60, v61
	s_waitcnt lgkmcnt(2)
	v_pk_mul_f32 v[30:31], v[30:31], v[228:229]
	v_pk_mul_f32 v[28:29], v[28:29], v[226:227]
	v_lshl_add_u64 v[62:63], v[186:187], 0, v[62:63]
	v_mfma_f32_16x16x32_bf16 v[52:55], v[234:237], v[92:95], v[52:55]
	global_store_dwordx2 v[62:63], v[0:1], off
	v_add_u32_e32 v0, s73, v68
	v_ashrrev_i32_e32 v1, 31, v0
	s_waitcnt lgkmcnt(0)
	v_mfma_f32_16x16x32_bf16 v[28:31], v[230:233], v[92:95], v[28:31]
	v_lshlrev_b64 v[0:1], 11, v[0:1]
	v_cvt_pk_bf16_f32 v60, v64, v65
	v_cvt_pk_bf16_f32 v61, v66, v67
	v_lshl_add_u64 v[0:1], v[186:187], 0, v[0:1]
	global_store_dwordx2 v[0:1], v[60:61], off
	s_cbranch_scc1 .LBB0_862

.LBB0_859:
	s_or_b64 exec, exec, s[96:97]
	s_add_i32 s78, s77, -1
	s_min_i32 s16, s78, s3
	s_lshl_b32 s16, s16, 5
	v_or_b32_e32 v0, s16, v191
	v_xad_u32 v1, v0, -1, s74
	v_cndmask_b32_e64 v0, v1, v0, s[4:5]
	v_add_u32_e32 v1, s16, v192
	v_xad_u32 v3, v1, -1, s74
	v_add_u32_e32 v0, s73, v0
	v_cndmask_b32_e64 v3, v3, v1, s[4:5]
	v_ashrrev_i32_e32 v1, 31, v0
	s_waitcnt vmcnt(7)
	ds_write_b128 v197, v[8:11] offset:26112
	v_mad_i64_i32 v[8:9], s[16:17], v0, s89, v[180:181]
	v_lshlrev_b64 v[0:1], 11, v[0:1]
	v_lshl_add_u64 v[0:1], v[182:183], 0, v[0:1]
	global_load_dwordx4 v[16:19], v[8:9], off
	global_load_dwordx4 v[24:27], v[0:1], off
	v_add_u32_e32 v0, s73, v3
	v_mad_i64_i32 v[0:1], s[16:17], v0, s89, v[184:185]
	global_load_dwordx4 v[8:11], v[0:1], off
	s_waitcnt lgkmcnt(0)
	s_barrier
	ds_read_b64_tr_b16 v[92:93], v199 offset:26112
	ds_read_b64_tr_b16 v[94:95], v199 offset:30464
	ds_read_b64 v[88:89], v200
	ds_read_b64 v[90:91], v200 offset:32
	ds_read_b64 v[80:81], v200 offset:64
	ds_read_b64 v[82:83], v200 offset:96
	ds_read_b64 v[72:73], v200 offset:128
	ds_read_b64 v[74:75], v200 offset:160
	ds_read_b64 v[60:61], v200 offset:192
	ds_read_b64 v[62:63], v200 offset:224
	ds_read_b64 v[84:85], v200 offset:4352
	ds_read_b64 v[86:87], v200 offset:4384
	ds_read_b64 v[76:77], v200 offset:4416
	ds_read_b64 v[78:79], v200 offset:4448
	ds_read_b64 v[68:69], v200 offset:4480
	ds_read_b64 v[70:71], v200 offset:4512
	ds_read_b64 v[64:65], v200 offset:4544
	ds_read_b64 v[66:67], v200 offset:4576
	ds_read_b64 v[100:101], v201 offset:13056
	ds_read_b64 v[102:103], v201 offset:13088
	ds_read_b64 v[96:97], v201 offset:8704
	ds_read_b64 v[98:99], v201 offset:8736
	ds_read_b64 v[108:109], v201 offset:8768
	ds_read_b64 v[110:111], v201 offset:8800
	ds_read_b64 v[112:113], v201 offset:13120
	ds_read_b64 v[114:115], v201 offset:13152
	s_waitcnt lgkmcnt(6)
	v_mfma_f32_16x16x32_bf16 v[100:103], v[100:103], v[84:87], 0
	s_waitcnt lgkmcnt(4)
	v_mfma_f32_16x16x32_bf16 v[104:107], v[96:99], v[88:91], 0
	s_waitcnt lgkmcnt(0)
	v_mfma_f32_16x16x32_bf16 v[100:103], v[112:115], v[76:79], v[100:103]
	ds_read_b64 v[112:113], v201 offset:8832
	ds_read_b64 v[114:115], v201 offset:8864
	ds_read_b64 v[116:117], v201 offset:13184
	ds_read_b64 v[118:119], v201 offset:13216
	v_mfma_f32_16x16x32_bf16 v[104:107], v[108:111], v[80:83], v[104:107]
	s_waitcnt lgkmcnt(0)
	v_mfma_f32_16x16x32_bf16 v[100:103], v[116:119], v[68:71], v[100:103]
	ds_read_b64 v[116:117], v201 offset:8896
	ds_read_b64 v[118:119], v201 offset:8928
	ds_read_b64 v[226:227], v201 offset:13248
	ds_read_b64 v[228:229], v201 offset:13280
	v_mov_b32_e32 v0, s93
	v_mfma_f32_16x16x32_bf16 v[96:99], v[96:99], v[84:87], 0
	v_mfma_f32_16x16x32_bf16 v[104:107], v[112:115], v[72:75], v[104:107]
	v_mfma_f32_16x16x32_bf16 v[96:99], v[108:111], v[76:79], v[96:99]
	s_waitcnt lgkmcnt(2)
	v_mfma_f32_16x16x32_bf16 v[104:107], v[116:119], v[60:63], v[104:107]
	s_waitcnt lgkmcnt(0)
	v_mfma_f32_16x16x32_bf16 v[100:103], v[226:229], v[64:67], v[100:103]
	v_mov_b32_e32 v226, s93
	s_nop 4
	v_cndmask_b32_e64 v0, v104, v0, s[8:9]
	v_cndmask_b32_e64 v0, v0, v104, s[10:11]
	v_mfma_f32_16x16x32_bf16 v[96:99], v[112:115], v[68:71], v[96:99]
	v_cndmask_b32_e64 v3, v106, 0, s[12:13]
	v_cndmask_b32_e64 v1, v100, v226, s[8:9]
	v_cndmask_b32_e64 v100, v1, v100, s[10:11]
	v_cndmask_b32_e64 v1, 0, v105, s[10:11]
	v_cndmask_b32_e64 v104, v107, 0, s[14:15]
	v_cvt_pk_bf16_f32 v0, v0, v1
	v_cvt_pk_bf16_f32 v1, v3, v104
	ds_read_b128 v[104:107], v202 offset:35328
	ds_read_b128 v[108:111], v202 offset:35392
	v_mfma_f32_16x16x32_bf16 v[96:99], v[116:119], v[64:67], v[96:99]
	v_cndmask_b32_e64 v101, 0, v101, s[10:11]
	v_cndmask_b32_e64 v102, v102, 0, s[12:13]
	v_cndmask_b32_e64 v103, v103, 0, s[14:15]
	v_mov_b32_e32 v3, v2
	s_waitcnt lgkmcnt(0)
	v_pk_mul_f32 v[110:111], v[54:55], v[110:111]
	s_nop 1
	v_cvt_pk_bf16_f32 v96, v96, v97
	v_cvt_pk_bf16_f32 v97, v98, v99
	v_cvt_pk_bf16_f32 v98, v100, v101
	v_cvt_pk_bf16_f32 v99, v102, v103
	v_mfma_f32_16x16x32_bf16 v[100:103], v[92:95], v[0:3], 0
	v_mul_f32_e64 v0, v58, v106
	v_mul_f32_e64 v1, v59, v107
	v_pk_mul_f32 v[106:107], v[52:53], v[108:109]
	v_pk_mul_f32 v[104:105], v[56:57], v[104:105]
	v_cvt_pk_bf16_f32 v106, v106, v107
	v_cvt_pk_bf16_f32 v107, v110, v111
	ds_read_b128 v[108:111], v202 offset:35456
	ds_read_b128 v[112:115], v202 offset:35520
	v_cvt_pk_bf16_f32 v104, v104, v105
	v_cvt_pk_bf16_f32 v105, v0, v1
	v_mfma_f32_16x16x32_bf16 v[96:99], v[92:95], v[96:99], 0
	s_waitcnt lgkmcnt(1)
	v_pk_mul_f32 v[0:1], v[50:51], v[110:111]
	v_pk_mul_f32 v[108:109], v[48:49], v[108:109]
	s_waitcnt lgkmcnt(0)
	v_pk_mul_f32 v[110:111], v[46:47], v[114:115]
	v_pk_mul_f32 v[112:113], v[44:45], v[112:113]
	v_cvt_pk_bf16_f32 v116, v108, v109
	v_cvt_pk_bf16_f32 v118, v112, v113
	v_cvt_pk_bf16_f32 v119, v110, v111
	ds_read_b128 v[108:111], v202 offset:35584
	ds_read_b128 v[112:115], v202 offset:35648
	v_cvt_pk_bf16_f32 v117, v0, v1
	v_mfma_f32_16x16x32_bf16 v[88:91], v[104:107], v[88:91], v[100:103]
	v_cndmask_b32_e64 v3, v222, v190, s[4:5]
	s_waitcnt lgkmcnt(1)
	v_pk_mul_f32 v[0:1], v[42:43], v[110:111]
	s_waitcnt lgkmcnt(0)
	v_pk_mul_f32 v[114:115], v[38:39], v[114:115]
	v_pk_mul_f32 v[110:111], v[36:37], v[112:113]
	v_pk_mul_f32 v[108:109], v[40:41], v[108:109]
	v_cvt_pk_bf16_f32 v110, v110, v111
	v_cvt_pk_bf16_f32 v111, v114, v115
	ds_read_b128 v[112:115], v202 offset:35712
	ds_read_b128 v[226:229], v202 offset:35776
	v_cvt_pk_bf16_f32 v108, v108, v109
	v_cvt_pk_bf16_f32 v109, v0, v1
	v_mfma_f32_16x16x32_bf16 v[84:87], v[104:107], v[84:87], v[96:99]
	s_waitcnt lgkmcnt(1)
	v_pk_mul_f32 v[0:1], v[34:35], v[114:115]
	s_waitcnt lgkmcnt(0)
	v_pk_mul_f32 v[228:229], v[30:31], v[228:229]
	v_pk_mul_f32 v[114:115], v[28:29], v[226:227]
	v_mfma_f32_16x16x32_bf16 v[80:83], v[116:119], v[80:83], v[88:91]
	v_cvt_pk_bf16_f32 v114, v114, v115
	v_cvt_pk_bf16_f32 v115, v228, v229
	ds_read_b128 v[226:229], v202 offset:34816
	ds_read_b64_tr_b16 v[232:233], v198 offset:21760
	ds_read_b64_tr_b16 v[230:231], v198 offset:17408
	ds_read_b64_tr_b16 v[234:235], v198 offset:17440
	v_pk_mul_f32 v[112:113], v[32:33], v[112:113]
	s_waitcnt lgkmcnt(3)
	v_pk_mul_f32 v[58:59], v[58:59], v[228:229]
	v_pk_mul_f32 v[56:57], v[56:57], v[226:227]
	ds_read_b128 v[226:229], v202 offset:34880
	ds_read_b64_tr_b16 v[236:237], v198 offset:21792
	s_waitcnt lgkmcnt(3)
	v_mfma_f32_16x16x32_bf16 v[56:59], v[230:233], v[92:95], v[56:59]
	v_cvt_pk_bf16_f32 v112, v112, v113
	v_cvt_pk_bf16_f32 v113, v0, v1
	s_waitcnt lgkmcnt(1)
	v_pk_mul_f32 v[54:55], v[54:55], v[228:229]
	v_pk_mul_f32 v[52:53], v[52:53], v[226:227]
	ds_read_b128 v[226:229], v202 offset:34944
	ds_read_b64_tr_b16 v[230:231], v198 offset:17472
	ds_read_b64_tr_b16 v[232:233], v198 offset:21824
	v_mfma_f32_16x16x32_bf16 v[76:79], v[116:119], v[76:79], v[84:87]
	v_xor_b32_e32 v1, 0xffffffef, v190
	s_waitcnt lgkmcnt(2)
	v_pk_mul_f32 v[50:51], v[50:51], v[228:229]
	v_pk_mul_f32 v[48:49], v[48:49], v[226:227]
	v_mfma_f32_16x16x32_bf16 v[72:75], v[108:111], v[72:75], v[80:83]
	v_add_u32_e32 v0, 16, v190
	v_add_u32_e32 v1, s74, v1
	s_waitcnt lgkmcnt(0)
	v_mfma_f32_16x16x32_bf16 v[48:51], v[230:233], v[92:95], v[48:51]
	ds_read_b128 v[226:229], v202 offset:35008
	ds_read_b64_tr_b16 v[230:231], v198 offset:17504
	ds_read_b64_tr_b16 v[232:233], v198 offset:21856
	s_waitcnt lgkmcnt(2)
	v_pk_mul_f32 v[46:47], v[46:47], v[228:229]
	v_pk_mul_f32 v[44:45], v[44:45], v[226:227]
	v_mfma_f32_16x16x32_bf16 v[68:71], v[108:111], v[68:71], v[76:79]
	s_waitcnt lgkmcnt(0)
	v_mfma_f32_16x16x32_bf16 v[44:47], v[230:233], v[92:95], v[44:47]
	ds_read_b128 v[226:229], v202 offset:35072
	ds_read_b64_tr_b16 v[230:231], v198 offset:17536
	ds_read_b64_tr_b16 v[232:233], v198 offset:21888
	s_waitcnt lgkmcnt(2)
	v_pk_mul_f32 v[42:43], v[42:43], v[228:229]
	v_pk_mul_f32 v[40:41], v[40:41], v[226:227]
	v_mfma_f32_16x16x32_bf16 v[60:63], v[112:115], v[60:63], v[72:75]
	s_waitcnt lgkmcnt(0)
	v_mfma_f32_16x16x32_bf16 v[40:43], v[230:233], v[92:95], v[40:43]
	ds_read_b128 v[226:229], v202 offset:35136
	ds_read_b64_tr_b16 v[230:231], v198 offset:17568
	ds_read_b64_tr_b16 v[232:233], v198 offset:21920
	s_waitcnt lgkmcnt(2)
	v_pk_mul_f32 v[38:39], v[38:39], v[228:229]
	v_pk_mul_f32 v[36:37], v[36:37], v[226:227]
	v_mfma_f32_16x16x32_bf16 v[64:67], v[112:115], v[64:67], v[68:71]
	s_waitcnt lgkmcnt(0)
	v_mfma_f32_16x16x32_bf16 v[36:39], v[230:233], v[92:95], v[36:39]
	ds_read_b128 v[226:229], v202 offset:35200
	ds_read_b64_tr_b16 v[230:231], v198 offset:17600
	ds_read_b64_tr_b16 v[232:233], v198 offset:21952
	v_cndmask_b32_e64 v68, v1, v0, s[4:5]
	v_cvt_pk_bf16_f32 v1, v62, v63
	s_waitcnt lgkmcnt(2)
	v_pk_mul_f32 v[34:35], v[34:35], v[228:229]
	v_pk_mul_f32 v[32:33], v[32:33], v[226:227]
	v_add_u32_e32 v62, s73, v3
	v_ashrrev_i32_e32 v63, 31, v62
	s_waitcnt lgkmcnt(0)
	v_mfma_f32_16x16x32_bf16 v[32:35], v[230:233], v[92:95], v[32:35]
	ds_read_b128 v[226:229], v202 offset:35264
	ds_read_b64_tr_b16 v[230:231], v198 offset:17632
	ds_read_b64_tr_b16 v[232:233], v198 offset:21984
	v_lshlrev_b64 v[62:63], 11, v[62:63]
	v_cvt_pk_bf16_f32 v0, v60, v61
	s_waitcnt lgkmcnt(2)
	v_pk_mul_f32 v[30:31], v[30:31], v[228:229]
	v_pk_mul_f32 v[28:29], v[28:29], v[226:227]
	v_lshl_add_u64 v[62:63], v[186:187], 0, v[62:63]
	v_mfma_f32_16x16x32_bf16 v[52:55], v[234:237], v[92:95], v[52:55]
	global_store_dwordx2 v[62:63], v[0:1], off
	v_add_u32_e32 v0, s73, v68
	v_ashrrev_i32_e32 v1, 31, v0
	s_waitcnt lgkmcnt(0)
	v_mfma_f32_16x16x32_bf16 v[28:31], v[230:233], v[92:95], v[28:31]
	v_lshlrev_b64 v[0:1], 11, v[0:1]
	v_cvt_pk_bf16_f32 v60, v64, v65
	v_cvt_pk_bf16_f32 v61, v66, v67
	v_lshl_add_u64 v[0:1], v[186:187], 0, v[0:1]
	global_store_dwordx2 v[0:1], v[60:61], off
	s_and_saveexec_b64 s[96:97], vcc
	s_cbranch_execz .LBB0_854
	s_waitcnt vmcnt(8)
	v_cvt_f32_f16_e32 v76, v20
	v_cvt_f32_f16_sdwa v75, v20 dst_sel:DWORD dst_unused:UNUSED_PAD src0_sel:WORD_1
	v_cvt_f32_f16_e32 v74, v21
	v_cvt_f32_f16_sdwa v73, v21 dst_sel:DWORD dst_unused:UNUSED_PAD src0_sel:WORD_1
	v_add_f32_dpp v0, v76, v76 row_shr:1 row_mask:0xf bank_mask:0xf bound_ctrl:1
	v_add_f32_dpp v1, v75, v75 row_shr:1 row_mask:0xf bank_mask:0xf bound_ctrl:1
	v_mov_b32_e32 v62, v2
	v_add_f32_dpp v0, v0, v0 row_shr:2 row_mask:0xf bank_mask:0xf bound_ctrl:1
	v_add_f32_dpp v1, v1, v1 row_shr:2 row_mask:0xf bank_mask:0xf bound_ctrl:1
	v_cvt_f32_f16_e32 v72, v22
	v_add_f32_dpp v0, v0, v0 row_shr:4 row_mask:0xf bank_mask:0xf bound_ctrl:1
	v_add_f32_dpp v20, v74, v74 row_shr:1 row_mask:0xf bank_mask:0xf bound_ctrl:1
	v_add_f32_dpp v1, v1, v1 row_shr:4 row_mask:0xf bank_mask:0xf bound_ctrl:1
	v_add_f32_dpp v0, v0, v0 row_shr:8 row_mask:0xf bank_mask:0xf bound_ctrl:1
	v_add_f32_dpp v20, v20, v20 row_shr:2 row_mask:0xf bank_mask:0xf bound_ctrl:1
	v_add_f32_dpp v1, v1, v1 row_shr:8 row_mask:0xf bank_mask:0xf bound_ctrl:1
	v_mov_b32_dpp v62, v0 row_bcast:15 row_mask:0xa bank_mask:0xf
	v_add_f32_e32 v78, v0, v62
	v_mov_b32_e32 v0, v2
	v_cvt_f32_f16_sdwa v71, v22 dst_sel:DWORD dst_unused:UNUSED_PAD src0_sel:WORD_1
	v_add_f32_dpp v21, v73, v73 row_shr:1 row_mask:0xf bank_mask:0xf bound_ctrl:1
	v_add_f32_dpp v20, v20, v20 row_shr:4 row_mask:0xf bank_mask:0xf bound_ctrl:1
	v_mov_b32_dpp v0, v1 row_bcast:15 row_mask:0xa bank_mask:0xf
	v_add_f32_dpp v21, v21, v21 row_shr:2 row_mask:0xf bank_mask:0xf bound_ctrl:1
	v_add_f32_dpp v20, v20, v20 row_shr:8 row_mask:0xf bank_mask:0xf bound_ctrl:1
	v_add_f32_e32 v79, v1, v0
	v_mov_b32_e32 v0, v2
	v_cvt_f32_f16_e32 v70, v23
	v_add_f32_dpp v22, v72, v72 row_shr:1 row_mask:0xf bank_mask:0xf bound_ctrl:1
	v_add_f32_dpp v21, v21, v21 row_shr:4 row_mask:0xf bank_mask:0xf bound_ctrl:1
	v_mov_b32_dpp v0, v20 row_bcast:15 row_mask:0xa bank_mask:0xf
	v_add_f32_dpp v22, v22, v22 row_shr:2 row_mask:0xf bank_mask:0xf bound_ctrl:1
	v_add_f32_dpp v21, v21, v21 row_shr:8 row_mask:0xf bank_mask:0xf bound_ctrl:1
	v_add_f32_e32 v80, v20, v0
	v_mov_b32_e32 v0, v2
	v_cvt_f32_f16_sdwa v3, v23 dst_sel:DWORD dst_unused:UNUSED_PAD src0_sel:WORD_1
	v_add_f32_dpp v23, v71, v71 row_shr:1 row_mask:0xf bank_mask:0xf bound_ctrl:1
	v_add_f32_dpp v22, v22, v22 row_shr:4 row_mask:0xf bank_mask:0xf bound_ctrl:1
	v_mov_b32_dpp v0, v21 row_bcast:15 row_mask:0xa bank_mask:0xf
	v_add_f32_dpp v23, v23, v23 row_shr:2 row_mask:0xf bank_mask:0xf bound_ctrl:1
	v_add_f32_dpp v22, v22, v22 row_shr:8 row_mask:0xf bank_mask:0xf bound_ctrl:1
	v_add_f32_e32 v81, v21, v0
	v_mov_b32_e32 v0, v2
	v_add_f32_dpp v60, v70, v70 row_shr:1 row_mask:0xf bank_mask:0xf bound_ctrl:1
	v_add_f32_dpp v23, v23, v23 row_shr:4 row_mask:0xf bank_mask:0xf bound_ctrl:1
	v_mov_b32_dpp v0, v22 row_bcast:15 row_mask:0xa bank_mask:0xf
	ds_bpermute_b32 v1, v193, v78
	v_add_f32_dpp v60, v60, v60 row_shr:2 row_mask:0xf bank_mask:0xf bound_ctrl:1
	v_add_f32_dpp v23, v23, v23 row_shr:8 row_mask:0xf bank_mask:0xf bound_ctrl:1
	v_add_f32_e32 v77, v22, v0
	v_mov_b32_e32 v0, v2
	v_add_f32_dpp v60, v60, v60 row_shr:4 row_mask:0xf bank_mask:0xf bound_ctrl:1
	v_add_f32_dpp v61, v3, v3 row_shr:1 row_mask:0xf bank_mask:0xf bound_ctrl:1
	v_mov_b32_dpp v0, v23 row_bcast:15 row_mask:0xa bank_mask:0xf
	v_add_f32_dpp v60, v60, v60 row_shr:8 row_mask:0xf bank_mask:0xf bound_ctrl:1
	v_add_f32_e32 v82, v23, v0
	v_mov_b32_e32 v0, v2
	v_add_f32_dpp v61, v61, v61 row_shr:2 row_mask:0xf bank_mask:0xf bound_ctrl:1
	ds_bpermute_b32 v22, v193, v80
	v_mov_b32_dpp v0, v60 row_bcast:15 row_mask:0xa bank_mask:0xf
	v_add_f32_e32 v83, v60, v0
	s_waitcnt lgkmcnt(1)
	v_sub_f32_e32 v0, v78, v1
	ds_bpermute_b32 v1, v193, v79
	v_med3_f32 v0, v0, s69, v189
	v_add_f32_dpp v61, v61, v61 row_shr:4 row_mask:0xf bank_mask:0xf bound_ctrl:1
	v_mul_f32_e32 v0, 0x3fb8aa3b, v0
	v_exp_f32_e32 v20, v0
	v_add_f32_dpp v61, v61, v61 row_shr:8 row_mask:0xf bank_mask:0xf bound_ctrl:1
	v_mov_b32_e32 v0, v2
	s_waitcnt lgkmcnt(0)
	v_sub_f32_e32 v1, v79, v1
	v_med3_f32 v1, v1, s69, v189
	v_mov_b32_dpp v0, v61 row_bcast:15 row_mask:0xa bank_mask:0xf
	v_add_f32_e32 v84, v61, v0
	v_mul_f32_e32 v1, 0x3fb8aa3b, v1
	v_exp_f32_e32 v21, v1
	ds_bpermute_b32 v1, v193, v81
	ds_bpermute_b32 v62, v193, v77
	ds_bpermute_b32 v63, v193, v82
	ds_bpermute_b32 v64, v193, v83
	ds_bpermute_b32 v65, v193, v84
	v_sub_f32_e32 v22, v80, v22
	s_waitcnt lgkmcnt(4)
	v_sub_f32_e32 v1, v81, v1
	s_waitcnt lgkmcnt(3)
	v_sub_f32_e32 v62, v77, v62
	s_waitcnt lgkmcnt(2)
	v_sub_f32_e32 v63, v82, v63
	s_waitcnt lgkmcnt(1)
	v_sub_f32_e32 v64, v83, v64
	s_waitcnt lgkmcnt(0)
	v_sub_f32_e32 v65, v84, v65
	v_med3_f32 v22, v22, s69, v189
	v_med3_f32 v1, v1, s69, v189
	v_med3_f32 v62, v62, s69, v189
	v_med3_f32 v63, v63, s69, v189
	v_med3_f32 v64, v64, s69, v189
	v_med3_f32 v65, v65, s69, v189
	v_mul_f32_e32 v22, 0x3fb8aa3b, v22
	v_mul_f32_e32 v1, 0x3fb8aa3b, v1
	v_mul_f32_e32 v62, 0x3fb8aa3b, v62
	v_mul_f32_e32 v63, 0x3fb8aa3b, v63
	v_mul_f32_e32 v64, 0x3fb8aa3b, v64
	v_mul_f32_e32 v65, 0x3fb8aa3b, v65
	v_exp_f32_e32 v60, v22
	v_exp_f32_e32 v61, v1
	v_exp_f32_e32 v62, v62
	v_exp_f32_e32 v63, v63
	v_exp_f32_e32 v64, v64
	v_exp_f32_e32 v65, v65
	ds_bpermute_b32 v0, v194, v20
	ds_bpermute_b32 v1, v194, v21
	ds_bpermute_b32 v22, v194, v60
	ds_bpermute_b32 v23, v194, v61
	ds_bpermute_b32 v68, v194, v62
	ds_bpermute_b32 v69, v194, v63
	ds_bpermute_b32 v66, v194, v64
	ds_bpermute_b32 v67, v194, v65
	s_and_saveexec_b64 s[16:17], s[6:7]
	s_cbranch_execz .LBB0_853
	v_mul_f32_e32 v78, 0x3fb8aa3b, v78
	v_mul_f32_e32 v79, 0x3fb8aa3b, v79
	v_mul_f32_e32 v80, 0x3fb8aa3b, v80
	v_mul_f32_e32 v81, 0x3fb8aa3b, v81
	v_exp_f32_e32 v78, v78
	v_exp_f32_e32 v79, v79
	v_exp_f32_e32 v80, v80
	v_exp_f32_e32 v81, v81
	v_mul_f32_e32 v77, 0x3fb8aa3b, v77
	ds_write_b128 v203, v[78:81]
	v_exp_f32_e32 v78, v77
	v_mul_f32_e32 v77, 0x3fb8aa3b, v82
	v_exp_f32_e32 v79, v77
	v_mul_f32_e32 v77, 0x3fb8aa3b, v83
	v_exp_f32_e32 v80, v77
	v_mul_f32_e32 v77, 0x3fb8aa3b, v84
	v_exp_f32_e32 v81, v77
	ds_write_b128 v203, v[78:81] offset:16
	s_branch .LBB0_853

.LBB0_868:
	s_or_b64 exec, exec, s[80:81]
	s_min_i32 s16, s35, s77
	s_lshl_b32 s16, s16, 5
	v_or_b32_e32 v0, s16, v127
	v_xad_u32 v1, v0, -1, s74
	v_cndmask_b32_e64 v0, v1, v0, s[4:5]
	v_add_u32_e32 v1, s16, v128
	v_xad_u32 v3, v1, -1, s74
	v_add_u32_e32 v0, s73, v0
	s_waitcnt vmcnt(8)
	ds_write_b128 v133, v[4:7] offset:61952
	v_cndmask_b32_e64 v3, v3, v1, s[4:5]
	v_ashrrev_i32_e32 v1, 31, v0
	v_mad_i64_i32 v[4:5], s[16:17], v0, s89, v[116:117]
	global_load_dwordx4 v[20:23], v[4:5], off
	v_lshlrev_b64 v[4:5], 10, v[0:1]
	v_lshl_add_u64 v[4:5], v[118:119], 0, v[4:5]
	v_mad_i64_i32 v[0:1], s[16:17], v0, s89, v[120:121]
	global_load_dwordx4 v[28:31], v[4:5], off
	global_load_dwordx4 v[12:15], v[0:1], off
	v_add_u32_e32 v0, s73, v3
	v_mad_i64_i32 v[0:1], s[16:17], v0, s89, v[122:123]
	global_load_dwordx4 v[4:7], v[0:1], off
	s_waitcnt lgkmcnt(0)
	s_barrier
	ds_read_b64_tr_b16 v[68:69], v140
	ds_read_b64_tr_b16 v[70:71], v140 offset:4352
	ds_read_b64 v[64:65], v135 offset:35840
	ds_read_b64 v[66:67], v135 offset:35872
	ds_read_b64 v[52:53], v135 offset:35904
	ds_read_b64 v[54:55], v135 offset:35936
	ds_read_b64 v[60:61], v135 offset:38144
	ds_read_b64 v[62:63], v135 offset:38176
	ds_read_b64 v[56:57], v135 offset:38208
	ds_read_b64 v[58:59], v135 offset:38240
	ds_read_b64 v[72:73], v136 offset:44544
	ds_read_b64 v[74:75], v136 offset:44576
	ds_read_b64 v[76:77], v136 offset:46848
	ds_read_b64 v[78:79], v136 offset:46880
	ds_read_b64 v[84:85], v136 offset:44608
	ds_read_b64 v[86:87], v136 offset:44640
	ds_read_b64 v[150:151], v136 offset:46912
	ds_read_b64 v[152:153], v136 offset:46944
	s_waitcnt lgkmcnt(6)
	v_mfma_f32_16x16x32_bf16 v[80:83], v[72:75], v[64:67], 0
	v_mov_b32_e32 v0, s93
	s_add_i32 s35, s35, 2
	v_subrev_u32_e32 v149, 64, v149
	s_waitcnt lgkmcnt(4)
	v_mfma_f32_16x16x32_bf16 v[76:79], v[76:79], v[60:63], 0
	s_cmp_ge_u32 s78, s3
	s_waitcnt lgkmcnt(2)
	v_mfma_f32_16x16x32_bf16 v[80:83], v[84:87], v[52:55], v[80:83]
	s_waitcnt lgkmcnt(0)
	v_mfma_f32_16x16x32_bf16 v[76:79], v[150:153], v[56:59], v[76:79]
	v_mov_b32_e32 v150, s93
	s_nop 4
	v_cndmask_b32_e64 v0, v80, v0, s[8:9]
	v_cndmask_b32_e64 v0, v0, v80, s[10:11]
	v_mfma_f32_16x16x32_bf16 v[72:75], v[72:75], v[60:63], 0
	v_cndmask_b32_e64 v3, v82, 0, s[12:13]
	v_cndmask_b32_e64 v1, v76, v150, s[8:9]
	v_cndmask_b32_e64 v76, v1, v76, s[10:11]
	v_cndmask_b32_e64 v1, 0, v81, s[10:11]
	v_cndmask_b32_e64 v80, v83, 0, s[14:15]
	v_mfma_f32_16x16x32_bf16 v[72:75], v[84:87], v[56:59], v[72:75]
	v_cvt_pk_bf16_f32 v0, v0, v1
	v_cvt_pk_bf16_f32 v1, v3, v80
	ds_read_b128 v[80:83], v141
	ds_read_b128 v[84:87], v142
	v_cndmask_b32_e64 v77, 0, v77, s[10:11]
	v_cndmask_b32_e64 v78, v78, 0, s[12:13]
	v_cndmask_b32_e64 v79, v79, 0, s[14:15]
	v_mov_b32_e32 v3, v2
	v_cvt_pk_bf16_f32 v72, v72, v73
	v_cvt_pk_bf16_f32 v73, v74, v75
	v_cvt_pk_bf16_f32 v74, v76, v77
	v_cvt_pk_bf16_f32 v75, v78, v79
	v_mfma_f32_16x16x32_bf16 v[76:79], v[68:71], v[0:3], 0
	s_waitcnt lgkmcnt(1)
	v_pk_mul_f32 v[0:1], v[50:51], v[82:83]
	s_waitcnt lgkmcnt(0)
	v_pk_mul_f32 v[86:87], v[46:47], v[86:87]
	v_pk_mul_f32 v[82:83], v[44:45], v[84:85]
	v_pk_mul_f32 v[80:81], v[48:49], v[80:81]
	v_cvt_pk_bf16_f32 v82, v82, v83
	v_cvt_pk_bf16_f32 v83, v86, v87
	ds_read_b128 v[84:87], v143
	ds_read_b128 v[150:153], v144
	v_cvt_pk_bf16_f32 v80, v80, v81
	v_cvt_pk_bf16_f32 v81, v0, v1
	v_mfma_f32_16x16x32_bf16 v[72:75], v[68:71], v[72:75], 0
	s_waitcnt lgkmcnt(1)
	v_pk_mul_f32 v[0:1], v[42:43], v[86:87]
	s_waitcnt lgkmcnt(0)
	v_pk_mul_f32 v[152:153], v[38:39], v[152:153]
	v_pk_mul_f32 v[86:87], v[36:37], v[150:151]
	v_pk_mul_f32 v[84:85], v[40:41], v[84:85]
	v_cvt_pk_bf16_f32 v86, v86, v87
	v_cvt_pk_bf16_f32 v87, v152, v153
	ds_read_b128 v[150:153], v145
	ds_read_b64_tr_b16 v[156:157], v138 offset:55552
	ds_read_b64_tr_b16 v[154:155], v138 offset:53248
	ds_read_b64_tr_b16 v[158:159], v138 offset:53280
	v_cvt_pk_bf16_f32 v84, v84, v85
	s_waitcnt lgkmcnt(3)
	v_pk_mul_f32 v[50:51], v[50:51], v[152:153]
	v_pk_mul_f32 v[48:49], v[48:49], v[150:151]
	ds_read_b128 v[150:153], v146
	ds_read_b64_tr_b16 v[160:161], v138 offset:55584
	v_cvt_pk_bf16_f32 v85, v0, v1
	v_mfma_f32_16x16x32_bf16 v[64:67], v[80:83], v[64:67], v[76:79]
	v_xor_b32_e32 v3, 0xffffffdf, v126
	s_waitcnt lgkmcnt(1)
	v_pk_mul_f32 v[46:47], v[46:47], v[152:153]
	v_pk_mul_f32 v[44:45], v[44:45], v[150:151]
	v_mfma_f32_16x16x32_bf16 v[48:51], v[154:157], v[68:71], v[48:51]
	ds_read_b128 v[150:153], v147
	ds_read_b64_tr_b16 v[154:155], v138 offset:53312
	ds_read_b64_tr_b16 v[156:157], v138 offset:55616
	v_add_u32_e32 v0, 32, v126
	v_add_u32_e32 v3, s74, v3
	v_mfma_f32_16x16x32_bf16 v[60:63], v[80:83], v[60:63], v[72:75]
	s_waitcnt lgkmcnt(2)
	v_pk_mul_f32 v[42:43], v[42:43], v[152:153]
	v_pk_mul_f32 v[40:41], v[40:41], v[150:151]
	v_cndmask_b32_e64 v3, v3, v0, s[4:5]
	v_mfma_f32_16x16x32_bf16 v[52:55], v[84:87], v[52:55], v[64:67]
	v_xor_b32_e32 v0, 0xffffffcf, v126
	v_add_u32_e32 v1, 48, v126
	v_add_u32_e32 v0, s74, v0
	s_waitcnt lgkmcnt(0)
	v_mfma_f32_16x16x32_bf16 v[40:43], v[154:157], v[68:71], v[40:43]
	ds_read_b128 v[150:153], v148
	ds_read_b64_tr_b16 v[154:155], v138 offset:53344
	ds_read_b64_tr_b16 v[156:157], v138 offset:55648
	v_add_u32_e32 v126, 64, v126
	s_waitcnt lgkmcnt(2)
	v_pk_mul_f32 v[38:39], v[38:39], v[152:153]
	v_mfma_f32_16x16x32_bf16 v[56:59], v[84:87], v[56:59], v[60:63]
	v_mul_f32_e64 v36, v36, v150
	v_mul_f32_e64 v37, v37, v151
	s_nop 0
	v_cndmask_b32_e64 v60, v0, v1, s[4:5]
	v_cvt_pk_bf16_f32 v1, v54, v55
	v_add_u32_e32 v54, s73, v3
	v_ashrrev_i32_e32 v55, 31, v54
	v_lshlrev_b64 v[54:55], 11, v[54:55]
	v_cvt_pk_bf16_f32 v0, v52, v53
	v_lshl_add_u64 v[54:55], v[124:125], 0, v[54:55]
	v_mfma_f32_16x16x32_bf16 v[44:47], v[158:161], v[68:71], v[44:47]
	global_store_dwordx2 v[54:55], v[0:1], off offset:1024
	v_add_u32_e32 v0, s73, v60
	v_ashrrev_i32_e32 v1, 31, v0
	s_waitcnt lgkmcnt(0)
	v_mfma_f32_16x16x32_bf16 v[36:39], v[154:157], v[68:71], v[36:39]
	v_lshlrev_b64 v[0:1], 11, v[0:1]
	v_cvt_pk_bf16_f32 v52, v56, v57
	v_cvt_pk_bf16_f32 v53, v58, v59
	v_lshl_add_u64 v[0:1], v[124:125], 0, v[0:1]
	global_store_dwordx2 v[0:1], v[52:53], off offset:1024
	s_cbranch_scc1 .LBB0_876

.LBB0_873:
	s_or_b64 exec, exec, s[80:81]
	s_add_i32 s78, s35, -1
	s_min_i32 s16, s78, s77
	s_lshl_b32 s16, s16, 5
	v_or_b32_e32 v0, s16, v127
	v_xad_u32 v1, v0, -1, s74
	v_cndmask_b32_e64 v0, v1, v0, s[4:5]
	v_add_u32_e32 v1, s16, v128
	v_xad_u32 v3, v1, -1, s74
	v_add_u32_e32 v0, s73, v0
	s_waitcnt vmcnt(8)
	ds_write_b128 v133, v[8:11] offset:26112
	v_cndmask_b32_e64 v3, v3, v1, s[4:5]
	v_ashrrev_i32_e32 v1, 31, v0
	v_mad_i64_i32 v[8:9], s[16:17], v0, s89, v[116:117]
	global_load_dwordx4 v[24:27], v[8:9], off
	v_lshlrev_b64 v[8:9], 10, v[0:1]
	v_lshl_add_u64 v[8:9], v[118:119], 0, v[8:9]
	v_mad_i64_i32 v[0:1], s[16:17], v0, s89, v[120:121]
	global_load_dwordx4 v[32:35], v[8:9], off
	global_load_dwordx4 v[16:19], v[0:1], off
	v_add_u32_e32 v0, s73, v3
	v_mad_i64_i32 v[0:1], s[16:17], v0, s89, v[122:123]
	global_load_dwordx4 v[8:11], v[0:1], off
	s_waitcnt lgkmcnt(0)
	s_barrier
	ds_read_b64_tr_b16 v[68:69], v134 offset:26112
	ds_read_b64_tr_b16 v[70:71], v134 offset:30464
	ds_read_b64 v[64:65], v135
	ds_read_b64 v[66:67], v135 offset:32
	ds_read_b64 v[52:53], v135 offset:64
	ds_read_b64 v[54:55], v135 offset:96
	ds_read_b64 v[60:61], v135 offset:2304
	ds_read_b64 v[62:63], v135 offset:2336
	ds_read_b64 v[56:57], v135 offset:2368
	ds_read_b64 v[58:59], v135 offset:2400
	ds_read_b64 v[72:73], v136 offset:8704
	ds_read_b64 v[74:75], v136 offset:8736
	ds_read_b64 v[76:77], v136 offset:11008
	ds_read_b64 v[78:79], v136 offset:11040
	ds_read_b64 v[84:85], v136 offset:8768
	ds_read_b64 v[86:87], v136 offset:8800
	ds_read_b64 v[150:151], v136 offset:11072
	ds_read_b64 v[152:153], v136 offset:11104
	s_waitcnt lgkmcnt(6)
	v_mfma_f32_16x16x32_bf16 v[80:83], v[72:75], v[64:67], 0
	v_mov_b32_e32 v0, s93
	s_waitcnt lgkmcnt(4)
	v_mfma_f32_16x16x32_bf16 v[76:79], v[76:79], v[60:63], 0
	s_waitcnt lgkmcnt(2)
	v_mfma_f32_16x16x32_bf16 v[80:83], v[84:87], v[52:55], v[80:83]
	s_waitcnt lgkmcnt(0)
	v_mfma_f32_16x16x32_bf16 v[76:79], v[150:153], v[56:59], v[76:79]
	v_mov_b32_e32 v150, s93
	s_nop 4
	v_cndmask_b32_e64 v0, v80, v0, s[8:9]
	v_cndmask_b32_e64 v0, v0, v80, s[10:11]
	v_mfma_f32_16x16x32_bf16 v[72:75], v[72:75], v[60:63], 0
	v_cndmask_b32_e64 v3, v82, 0, s[12:13]
	v_cndmask_b32_e64 v1, v76, v150, s[8:9]
	v_cndmask_b32_e64 v76, v1, v76, s[10:11]
	v_cndmask_b32_e64 v1, 0, v81, s[10:11]
	v_cndmask_b32_e64 v80, v83, 0, s[14:15]
	v_mfma_f32_16x16x32_bf16 v[72:75], v[84:87], v[56:59], v[72:75]
	v_cvt_pk_bf16_f32 v0, v0, v1
	v_cvt_pk_bf16_f32 v1, v3, v80
	ds_read_b128 v[80:83], v137 offset:35328
	ds_read_b128 v[84:87], v137 offset:35392
	v_cndmask_b32_e64 v77, 0, v77, s[10:11]
	v_cndmask_b32_e64 v78, v78, 0, s[12:13]
	v_cndmask_b32_e64 v79, v79, 0, s[14:15]
	v_mov_b32_e32 v3, v2
	v_cvt_pk_bf16_f32 v72, v72, v73
	v_cvt_pk_bf16_f32 v73, v74, v75
	v_cvt_pk_bf16_f32 v74, v76, v77
	v_cvt_pk_bf16_f32 v75, v78, v79
	v_mfma_f32_16x16x32_bf16 v[76:79], v[68:71], v[0:3], 0
	s_waitcnt lgkmcnt(1)
	v_pk_mul_f32 v[0:1], v[50:51], v[82:83]
	s_waitcnt lgkmcnt(0)
	v_pk_mul_f32 v[86:87], v[46:47], v[86:87]
	v_pk_mul_f32 v[82:83], v[44:45], v[84:85]
	v_pk_mul_f32 v[80:81], v[48:49], v[80:81]
	v_cvt_pk_bf16_f32 v82, v82, v83
	v_cvt_pk_bf16_f32 v83, v86, v87
	ds_read_b128 v[84:87], v137 offset:35456
	ds_read_b128 v[150:153], v137 offset:35520
	v_cvt_pk_bf16_f32 v80, v80, v81
	v_cvt_pk_bf16_f32 v81, v0, v1
	v_mfma_f32_16x16x32_bf16 v[72:75], v[68:71], v[72:75], 0
	s_waitcnt lgkmcnt(1)
	v_pk_mul_f32 v[0:1], v[42:43], v[86:87]
	s_waitcnt lgkmcnt(0)
	v_pk_mul_f32 v[152:153], v[38:39], v[152:153]
	v_pk_mul_f32 v[86:87], v[36:37], v[150:151]
	v_pk_mul_f32 v[84:85], v[40:41], v[84:85]
	v_cvt_pk_bf16_f32 v86, v86, v87
	v_cvt_pk_bf16_f32 v87, v152, v153
	ds_read_b128 v[150:153], v137 offset:34816
	ds_read_b64_tr_b16 v[156:157], v138 offset:19712
	ds_read_b64_tr_b16 v[154:155], v138 offset:17408
	ds_read_b64_tr_b16 v[158:159], v138 offset:17440
	v_cvt_pk_bf16_f32 v84, v84, v85
	s_waitcnt lgkmcnt(3)
	v_pk_mul_f32 v[50:51], v[50:51], v[152:153]
	v_pk_mul_f32 v[48:49], v[48:49], v[150:151]
	ds_read_b128 v[150:153], v137 offset:34880
	ds_read_b64_tr_b16 v[160:161], v138 offset:19744
	v_cvt_pk_bf16_f32 v85, v0, v1
	v_mfma_f32_16x16x32_bf16 v[64:67], v[80:83], v[64:67], v[76:79]
	v_xor_b32_e32 v1, 0xffffffef, v126
	s_waitcnt lgkmcnt(1)
	v_pk_mul_f32 v[46:47], v[46:47], v[152:153]
	v_pk_mul_f32 v[44:45], v[44:45], v[150:151]
	v_mfma_f32_16x16x32_bf16 v[48:51], v[154:157], v[68:71], v[48:51]
	ds_read_b128 v[150:153], v137 offset:34944
	ds_read_b64_tr_b16 v[154:155], v138 offset:17472
	ds_read_b64_tr_b16 v[156:157], v138 offset:19776
	v_add_u32_e32 v0, 16, v126
	v_cndmask_b32_e64 v3, v149, v126, s[4:5]
	v_mfma_f32_16x16x32_bf16 v[60:63], v[80:83], v[60:63], v[72:75]
	s_waitcnt lgkmcnt(2)
	v_pk_mul_f32 v[42:43], v[42:43], v[152:153]
	v_pk_mul_f32 v[40:41], v[40:41], v[150:151]
	v_add_u32_e32 v1, s74, v1
	v_mfma_f32_16x16x32_bf16 v[52:55], v[84:87], v[52:55], v[64:67]
	s_waitcnt lgkmcnt(0)
	v_mfma_f32_16x16x32_bf16 v[40:43], v[154:157], v[68:71], v[40:43]
	ds_read_b128 v[150:153], v137 offset:35008
	ds_read_b64_tr_b16 v[154:155], v138 offset:17504
	ds_read_b64_tr_b16 v[156:157], v138 offset:19808
	s_waitcnt lgkmcnt(2)
	v_pk_mul_f32 v[38:39], v[38:39], v[152:153]
	v_mfma_f32_16x16x32_bf16 v[56:59], v[84:87], v[56:59], v[60:63]
	v_mul_f32_e64 v36, v36, v150
	v_mul_f32_e64 v37, v37, v151
	s_nop 0
	v_cndmask_b32_e64 v60, v1, v0, s[4:5]
	v_cvt_pk_bf16_f32 v1, v54, v55
	v_add_u32_e32 v54, s73, v3
	v_ashrrev_i32_e32 v55, 31, v54
	v_lshlrev_b64 v[54:55], 11, v[54:55]
	v_cvt_pk_bf16_f32 v0, v52, v53
	v_lshl_add_u64 v[54:55], v[124:125], 0, v[54:55]
	v_mfma_f32_16x16x32_bf16 v[44:47], v[158:161], v[68:71], v[44:47]
	global_store_dwordx2 v[54:55], v[0:1], off offset:1024
	v_add_u32_e32 v0, s73, v60
	v_ashrrev_i32_e32 v1, 31, v0
	s_waitcnt lgkmcnt(0)
	v_mfma_f32_16x16x32_bf16 v[36:39], v[154:157], v[68:71], v[36:39]
	v_lshlrev_b64 v[0:1], 11, v[0:1]
	v_cvt_pk_bf16_f32 v52, v56, v57
	v_cvt_pk_bf16_f32 v53, v58, v59
	v_lshl_add_u64 v[0:1], v[124:125], 0, v[0:1]
	global_store_dwordx2 v[0:1], v[52:53], off offset:1024
	s_and_saveexec_b64 s[80:81], vcc
	s_cbranch_execz .LBB0_868
	s_waitcnt vmcnt(10)
	v_cvt_f32_f16_e32 v0, v28
	v_cvt_f32_f16_sdwa v1, v28 dst_sel:DWORD dst_unused:UNUSED_PAD src0_sel:WORD_1
	v_cvt_f32_f16_e32 v3, v29
	v_cvt_f32_f16_sdwa v28, v29 dst_sel:DWORD dst_unused:UNUSED_PAD src0_sel:WORD_1
	v_add_f32_dpp v0, v0, v0 row_shr:1 row_mask:0xf bank_mask:0xf bound_ctrl:1
	v_add_f32_dpp v1, v1, v1 row_shr:1 row_mask:0xf bank_mask:0xf bound_ctrl:1
	v_mov_b32_e32 v53, v2
	v_add_f32_dpp v0, v0, v0 row_shr:2 row_mask:0xf bank_mask:0xf bound_ctrl:1
	v_add_f32_dpp v1, v1, v1 row_shr:2 row_mask:0xf bank_mask:0xf bound_ctrl:1
	v_cvt_f32_f16_e32 v29, v30
	v_add_f32_dpp v0, v0, v0 row_shr:4 row_mask:0xf bank_mask:0xf bound_ctrl:1
	v_add_f32_dpp v3, v3, v3 row_shr:1 row_mask:0xf bank_mask:0xf bound_ctrl:1
	v_add_f32_dpp v1, v1, v1 row_shr:4 row_mask:0xf bank_mask:0xf bound_ctrl:1
	v_add_f32_dpp v0, v0, v0 row_shr:8 row_mask:0xf bank_mask:0xf bound_ctrl:1
	v_add_f32_dpp v3, v3, v3 row_shr:2 row_mask:0xf bank_mask:0xf bound_ctrl:1
	v_add_f32_dpp v1, v1, v1 row_shr:8 row_mask:0xf bank_mask:0xf bound_ctrl:1
	v_mov_b32_dpp v53, v0 row_bcast:15 row_mask:0xa bank_mask:0xf
	v_add_f32_e32 v62, v0, v53
	v_mov_b32_e32 v0, v2
	v_cvt_f32_f16_sdwa v30, v30 dst_sel:DWORD dst_unused:UNUSED_PAD src0_sel:WORD_1
	v_add_f32_dpp v28, v28, v28 row_shr:1 row_mask:0xf bank_mask:0xf bound_ctrl:1
	v_add_f32_dpp v3, v3, v3 row_shr:4 row_mask:0xf bank_mask:0xf bound_ctrl:1
	v_mov_b32_dpp v0, v1 row_bcast:15 row_mask:0xa bank_mask:0xf
	v_add_f32_dpp v28, v28, v28 row_shr:2 row_mask:0xf bank_mask:0xf bound_ctrl:1
	v_add_f32_dpp v3, v3, v3 row_shr:8 row_mask:0xf bank_mask:0xf bound_ctrl:1
	v_add_f32_e32 v63, v1, v0
	v_mov_b32_e32 v0, v2
	v_cvt_f32_f16_e32 v52, v31
	v_add_f32_dpp v29, v29, v29 row_shr:1 row_mask:0xf bank_mask:0xf bound_ctrl:1
	v_add_f32_dpp v28, v28, v28 row_shr:4 row_mask:0xf bank_mask:0xf bound_ctrl:1
	v_mov_b32_dpp v0, v3 row_bcast:15 row_mask:0xa bank_mask:0xf
	v_add_f32_dpp v29, v29, v29 row_shr:2 row_mask:0xf bank_mask:0xf bound_ctrl:1
	v_add_f32_dpp v28, v28, v28 row_shr:8 row_mask:0xf bank_mask:0xf bound_ctrl:1
	v_add_f32_e32 v64, v3, v0
	v_mov_b32_e32 v0, v2
	v_add_f32_dpp v30, v30, v30 row_shr:1 row_mask:0xf bank_mask:0xf bound_ctrl:1
	v_add_f32_dpp v29, v29, v29 row_shr:4 row_mask:0xf bank_mask:0xf bound_ctrl:1
	v_mov_b32_dpp v0, v28 row_bcast:15 row_mask:0xa bank_mask:0xf
	v_add_f32_dpp v30, v30, v30 row_shr:2 row_mask:0xf bank_mask:0xf bound_ctrl:1
	v_add_f32_dpp v29, v29, v29 row_shr:8 row_mask:0xf bank_mask:0xf bound_ctrl:1
	v_add_f32_e32 v65, v28, v0
	v_mov_b32_e32 v0, v2
	v_add_f32_dpp v52, v52, v52 row_shr:1 row_mask:0xf bank_mask:0xf bound_ctrl:1
	v_add_f32_dpp v30, v30, v30 row_shr:4 row_mask:0xf bank_mask:0xf bound_ctrl:1
	v_mov_b32_dpp v0, v29 row_bcast:15 row_mask:0xa bank_mask:0xf
	ds_bpermute_b32 v1, v129, v62
	v_add_f32_dpp v52, v52, v52 row_shr:2 row_mask:0xf bank_mask:0xf bound_ctrl:1
	v_add_f32_dpp v30, v30, v30 row_shr:8 row_mask:0xf bank_mask:0xf bound_ctrl:1
	v_add_f32_e32 v3, v29, v0
	v_mov_b32_e32 v0, v2
	v_add_f32_dpp v52, v52, v52 row_shr:4 row_mask:0xf bank_mask:0xf bound_ctrl:1
	v_cvt_f32_f16_sdwa v31, v31 dst_sel:DWORD dst_unused:UNUSED_PAD src0_sel:WORD_1
	v_mov_b32_dpp v0, v30 row_bcast:15 row_mask:0xa bank_mask:0xf
	v_add_f32_dpp v52, v52, v52 row_shr:8 row_mask:0xf bank_mask:0xf bound_ctrl:1
	v_add_f32_e32 v66, v30, v0
	v_mov_b32_e32 v0, v2
	v_add_f32_dpp v31, v31, v31 row_shr:1 row_mask:0xf bank_mask:0xf bound_ctrl:1
	ds_bpermute_b32 v30, v129, v64
	v_mov_b32_dpp v0, v52 row_bcast:15 row_mask:0xa bank_mask:0xf
	v_add_f32_e32 v67, v52, v0
	s_waitcnt lgkmcnt(1)
	v_sub_f32_e32 v0, v62, v1
	ds_bpermute_b32 v1, v129, v63
	v_add_f32_dpp v31, v31, v31 row_shr:2 row_mask:0xf bank_mask:0xf bound_ctrl:1
	v_med3_f32 v0, v0, s69, v189
	v_mul_f32_e32 v0, 0x3fb8aa3b, v0
	v_add_f32_dpp v31, v31, v31 row_shr:4 row_mask:0xf bank_mask:0xf bound_ctrl:1
	v_exp_f32_e32 v28, v0
	v_mov_b32_e32 v0, v2
	v_add_f32_dpp v31, v31, v31 row_shr:8 row_mask:0xf bank_mask:0xf bound_ctrl:1
	s_waitcnt lgkmcnt(0)
	v_sub_f32_e32 v1, v63, v1
	ds_bpermute_b32 v56, v129, v67
	v_mov_b32_dpp v0, v31 row_bcast:15 row_mask:0xa bank_mask:0xf
	v_med3_f32 v1, v1, s69, v189
	v_add_f32_e32 v68, v31, v0
	v_mul_f32_e32 v1, 0x3fb8aa3b, v1
	v_exp_f32_e32 v29, v1
	ds_bpermute_b32 v1, v129, v65
	ds_bpermute_b32 v54, v129, v3
	ds_bpermute_b32 v55, v129, v66
	ds_bpermute_b32 v57, v129, v68
	s_waitcnt lgkmcnt(4)
	v_sub_f32_e32 v56, v67, v56
	v_med3_f32 v56, v56, s69, v189
	v_mul_f32_e32 v56, 0x3fb8aa3b, v56
	v_sub_f32_e32 v30, v64, v30
	s_waitcnt lgkmcnt(3)
	v_sub_f32_e32 v1, v65, v1
	s_waitcnt lgkmcnt(2)
	v_sub_f32_e32 v54, v3, v54
	s_waitcnt lgkmcnt(1)
	v_sub_f32_e32 v55, v66, v55
	v_exp_f32_e32 v58, v56
	s_waitcnt lgkmcnt(0)
	v_sub_f32_e32 v56, v68, v57
	v_med3_f32 v30, v30, s69, v189
	v_med3_f32 v1, v1, s69, v189
	v_med3_f32 v54, v54, s69, v189
	v_med3_f32 v55, v55, s69, v189
	v_med3_f32 v56, v56, s69, v189
	v_mul_f32_e32 v30, 0x3fb8aa3b, v30
	v_mul_f32_e32 v1, 0x3fb8aa3b, v1
	v_mul_f32_e32 v54, 0x3fb8aa3b, v54
	v_mul_f32_e32 v55, 0x3fb8aa3b, v55
	v_mul_f32_e32 v56, 0x3fb8aa3b, v56
	v_exp_f32_e32 v30, v30
	v_exp_f32_e32 v31, v1
	v_exp_f32_e32 v54, v54
	v_exp_f32_e32 v55, v55
	v_exp_f32_e32 v59, v56
	ds_bpermute_b32 v0, v130, v28
	ds_bpermute_b32 v1, v130, v29
	ds_bpermute_b32 v52, v130, v30
	ds_bpermute_b32 v53, v130, v31
	ds_bpermute_b32 v60, v130, v54
	ds_bpermute_b32 v61, v130, v55
	ds_bpermute_b32 v56, v130, v58
	ds_bpermute_b32 v57, v130, v59
	s_and_saveexec_b64 s[16:17], s[6:7]
	s_cbranch_execz .LBB0_867
	v_mul_f32_e32 v62, 0x3fb8aa3b, v62
	v_mul_f32_e32 v63, 0x3fb8aa3b, v63
	v_mul_f32_e32 v64, 0x3fb8aa3b, v64
	v_mul_f32_e32 v65, 0x3fb8aa3b, v65
	v_exp_f32_e32 v62, v62
	v_exp_f32_e32 v63, v63
	v_exp_f32_e32 v64, v64
	v_exp_f32_e32 v65, v65
	v_mul_f32_e32 v3, 0x3fb8aa3b, v3
	ds_write_b128 v139, v[62:65]
	v_exp_f32_e32 v62, v3
	v_mul_f32_e32 v3, 0x3fb8aa3b, v66
	v_exp_f32_e32 v63, v3
	v_mul_f32_e32 v3, 0x3fb8aa3b, v67
	v_exp_f32_e32 v64, v3
	v_mul_f32_e32 v3, 0x3fb8aa3b, v68
	v_exp_f32_e32 v65, v3
	ds_write_b128 v139, v[62:65] offset:16
	s_branch .LBB0_867

.LBB0_882:
	s_or_b64 exec, exec, s[56:57]
	s_min_i32 s16, s28, s35
	s_lshl_b32 s16, s16, 5
	v_or_b32_e32 v0, s16, v89
	v_xad_u32 v1, v0, -1, s74
	v_cndmask_b32_e64 v0, v1, v0, s[4:5]
	v_add_u32_e32 v1, s16, v90
	v_xad_u32 v3, v1, -1, s74
	v_add_u32_e32 v0, s73, v0
	v_cndmask_b32_e64 v3, v3, v1, s[4:5]
	v_ashrrev_i32_e32 v1, 31, v0
	s_waitcnt vmcnt(7)
	ds_write_b128 v95, v[4:7] offset:61952
	v_mad_i64_i32 v[4:5], s[16:17], v0, s89, v[80:81]
	v_lshlrev_b64 v[0:1], 11, v[0:1]
	v_lshl_add_u64 v[0:1], v[82:83], 0, v[0:1]
	global_load_dwordx4 v[12:15], v[4:5], off
	global_load_dwordx4 v[20:23], v[0:1], off
	v_add_u32_e32 v0, s73, v3
	v_mad_i64_i32 v[0:1], s[16:17], v0, s89, v[84:85]
	global_load_dwordx4 v[4:7], v[0:1], off
	s_waitcnt lgkmcnt(0)
	s_barrier
	ds_read_b64_tr_b16 v[60:61], v102
	ds_read_b64_tr_b16 v[62:63], v102 offset:4352
	ds_read_b64 v[56:57], v97 offset:35840
	ds_read_b64 v[58:59], v97 offset:35872
	ds_read_b64 v[44:45], v97 offset:35904
	ds_read_b64 v[46:47], v97 offset:35936
	ds_read_b64 v[52:53], v97 offset:38144
	ds_read_b64 v[54:55], v97 offset:38176
	ds_read_b64 v[48:49], v97 offset:38208
	ds_read_b64 v[50:51], v97 offset:38240
	ds_read_b64 v[64:65], v98 offset:44544
	ds_read_b64 v[66:67], v98 offset:44576
	ds_read_b64 v[68:69], v98 offset:46848
	ds_read_b64 v[70:71], v98 offset:46880
	ds_read_b64 v[76:77], v98 offset:44608
	ds_read_b64 v[78:79], v98 offset:44640
	ds_read_b64 v[112:113], v98 offset:46912
	ds_read_b64 v[114:115], v98 offset:46944
	s_waitcnt lgkmcnt(6)
	v_mfma_f32_16x16x32_bf16 v[72:75], v[64:67], v[56:59], 0
	v_mov_b32_e32 v0, s93
	s_add_i32 s28, s28, 2
	v_subrev_u32_e32 v111, 64, v111
	s_waitcnt lgkmcnt(4)
	v_mfma_f32_16x16x32_bf16 v[68:71], v[68:71], v[52:55], 0
	s_cmp_lt_u32 s58, s3
	s_waitcnt lgkmcnt(2)
	v_mfma_f32_16x16x32_bf16 v[72:75], v[76:79], v[44:47], v[72:75]
	s_waitcnt lgkmcnt(0)
	v_mfma_f32_16x16x32_bf16 v[68:71], v[112:115], v[48:51], v[68:71]
	v_mov_b32_e32 v112, s93
	s_nop 4
	v_cndmask_b32_e64 v0, v72, v0, s[8:9]
	v_cndmask_b32_e64 v0, v0, v72, s[10:11]
	v_mfma_f32_16x16x32_bf16 v[64:67], v[64:67], v[52:55], 0
	v_cndmask_b32_e64 v3, v74, 0, s[12:13]
	v_cndmask_b32_e64 v1, v68, v112, s[8:9]
	v_cndmask_b32_e64 v68, v1, v68, s[10:11]
	v_cndmask_b32_e64 v1, 0, v73, s[10:11]
	v_cndmask_b32_e64 v72, v75, 0, s[14:15]
	v_mfma_f32_16x16x32_bf16 v[64:67], v[76:79], v[48:51], v[64:67]
	v_cvt_pk_bf16_f32 v0, v0, v1
	v_cvt_pk_bf16_f32 v1, v3, v72
	ds_read_b128 v[72:75], v103
	ds_read_b128 v[76:79], v104
	v_cndmask_b32_e64 v69, 0, v69, s[10:11]
	v_cndmask_b32_e64 v70, v70, 0, s[12:13]
	v_cndmask_b32_e64 v71, v71, 0, s[14:15]
	v_mov_b32_e32 v3, v2
	v_cvt_pk_bf16_f32 v64, v64, v65
	v_cvt_pk_bf16_f32 v65, v66, v67
	v_cvt_pk_bf16_f32 v66, v68, v69
	v_cvt_pk_bf16_f32 v67, v70, v71
	v_mfma_f32_16x16x32_bf16 v[68:71], v[60:63], v[0:3], 0
	s_waitcnt lgkmcnt(1)
	v_pk_mul_f32 v[0:1], v[42:43], v[74:75]
	s_waitcnt lgkmcnt(0)
	v_pk_mul_f32 v[78:79], v[38:39], v[78:79]
	v_pk_mul_f32 v[74:75], v[36:37], v[76:77]
	v_pk_mul_f32 v[72:73], v[40:41], v[72:73]
	v_cvt_pk_bf16_f32 v74, v74, v75
	v_cvt_pk_bf16_f32 v75, v78, v79
	ds_read_b128 v[76:79], v105
	ds_read_b128 v[112:115], v106
	v_cvt_pk_bf16_f32 v72, v72, v73
	v_cvt_pk_bf16_f32 v73, v0, v1
	v_mfma_f32_16x16x32_bf16 v[64:67], v[60:63], v[64:67], 0
	s_waitcnt lgkmcnt(1)
	v_pk_mul_f32 v[0:1], v[30:31], v[78:79]
	s_waitcnt lgkmcnt(0)
	v_pk_mul_f32 v[114:115], v[34:35], v[114:115]
	v_pk_mul_f32 v[78:79], v[32:33], v[112:113]
	v_pk_mul_f32 v[76:77], v[28:29], v[76:77]
	v_cvt_pk_bf16_f32 v78, v78, v79
	v_cvt_pk_bf16_f32 v79, v114, v115
	ds_read_b128 v[112:115], v107
	ds_read_b64_tr_b16 v[118:119], v100 offset:55552
	ds_read_b64_tr_b16 v[116:117], v100 offset:53248
	ds_read_b64_tr_b16 v[120:121], v100 offset:53280
	v_cvt_pk_bf16_f32 v76, v76, v77
	s_waitcnt lgkmcnt(3)
	v_pk_mul_f32 v[42:43], v[42:43], v[114:115]
	v_pk_mul_f32 v[40:41], v[40:41], v[112:113]
	ds_read_b128 v[112:115], v108
	ds_read_b64_tr_b16 v[122:123], v100 offset:55584
	v_cvt_pk_bf16_f32 v77, v0, v1
	v_mfma_f32_16x16x32_bf16 v[56:59], v[72:75], v[56:59], v[68:71]
	v_xor_b32_e32 v3, 0xffffffdf, v88
	s_waitcnt lgkmcnt(1)
	v_pk_mul_f32 v[38:39], v[38:39], v[114:115]
	v_pk_mul_f32 v[36:37], v[36:37], v[112:113]
	v_mfma_f32_16x16x32_bf16 v[40:43], v[116:119], v[60:63], v[40:43]
	ds_read_b128 v[112:115], v109
	ds_read_b64_tr_b16 v[116:117], v100 offset:53312
	ds_read_b64_tr_b16 v[118:119], v100 offset:55616
	v_add_u32_e32 v0, 32, v88
	v_add_u32_e32 v3, s74, v3
	v_mfma_f32_16x16x32_bf16 v[52:55], v[72:75], v[52:55], v[64:67]
	s_waitcnt lgkmcnt(2)
	v_pk_mul_f32 v[30:31], v[30:31], v[114:115]
	v_pk_mul_f32 v[28:29], v[28:29], v[112:113]
	v_cndmask_b32_e64 v3, v3, v0, s[4:5]
	v_mfma_f32_16x16x32_bf16 v[44:47], v[76:79], v[44:47], v[56:59]
	v_xor_b32_e32 v0, 0xffffffcf, v88
	v_add_u32_e32 v1, 48, v88
	v_add_u32_e32 v0, s74, v0
	s_waitcnt lgkmcnt(0)
	v_mfma_f32_16x16x32_bf16 v[28:31], v[116:119], v[60:63], v[28:31]
	ds_read_b128 v[112:115], v110
	ds_read_b64_tr_b16 v[116:117], v100 offset:53344
	ds_read_b64_tr_b16 v[118:119], v100 offset:55648
	v_add_u32_e32 v88, 64, v88
	s_waitcnt lgkmcnt(2)
	v_pk_mul_f32 v[34:35], v[34:35], v[114:115]
	v_mfma_f32_16x16x32_bf16 v[48:51], v[76:79], v[48:51], v[52:55]
	v_mul_f32_e64 v32, v32, v112
	v_mul_f32_e64 v33, v33, v113
	s_nop 0
	v_cndmask_b32_e64 v52, v0, v1, s[4:5]
	v_cvt_pk_bf16_f32 v1, v46, v47
	v_add_u32_e32 v46, s73, v3
	v_ashrrev_i32_e32 v47, 31, v46
	v_lshlrev_b64 v[46:47], 11, v[46:47]
	v_cvt_pk_bf16_f32 v0, v44, v45
	v_lshl_add_u64 v[46:47], v[86:87], 0, v[46:47]
	v_mfma_f32_16x16x32_bf16 v[36:39], v[120:123], v[60:63], v[36:39]
	global_store_dwordx2 v[46:47], v[0:1], off
	v_add_u32_e32 v0, s73, v52
	v_ashrrev_i32_e32 v1, 31, v0
	s_waitcnt lgkmcnt(0)
	v_mfma_f32_16x16x32_bf16 v[32:35], v[116:119], v[60:63], v[32:35]
	v_lshlrev_b64 v[0:1], 11, v[0:1]
	v_cvt_pk_bf16_f32 v44, v48, v49
	v_cvt_pk_bf16_f32 v45, v50, v51
	v_lshl_add_u64 v[0:1], v[86:87], 0, v[0:1]
	global_store_dwordx2 v[0:1], v[44:45], off
	s_cbranch_scc0 .LBB0_815

.LBB0_887:
	s_or_b64 exec, exec, s[56:57]
	s_add_i32 s58, s28, -1
	s_min_i32 s16, s58, s35
	s_lshl_b32 s16, s16, 5
	v_or_b32_e32 v0, s16, v89
	v_xad_u32 v1, v0, -1, s74
	v_cndmask_b32_e64 v0, v1, v0, s[4:5]
	v_add_u32_e32 v1, s16, v90
	v_xad_u32 v3, v1, -1, s74
	v_add_u32_e32 v0, s73, v0
	v_cndmask_b32_e64 v3, v3, v1, s[4:5]
	v_ashrrev_i32_e32 v1, 31, v0
	s_waitcnt vmcnt(7)
	ds_write_b128 v95, v[8:11] offset:26112
	v_mad_i64_i32 v[8:9], s[16:17], v0, s89, v[80:81]
	v_lshlrev_b64 v[0:1], 11, v[0:1]
	v_lshl_add_u64 v[0:1], v[82:83], 0, v[0:1]
	global_load_dwordx4 v[16:19], v[8:9], off
	global_load_dwordx4 v[24:27], v[0:1], off
	v_add_u32_e32 v0, s73, v3
	v_mad_i64_i32 v[0:1], s[16:17], v0, s89, v[84:85]
	global_load_dwordx4 v[8:11], v[0:1], off
	s_waitcnt lgkmcnt(0)
	s_barrier
	ds_read_b64_tr_b16 v[60:61], v96 offset:26112
	ds_read_b64_tr_b16 v[62:63], v96 offset:30464
	ds_read_b64 v[56:57], v97
	ds_read_b64 v[58:59], v97 offset:32
	ds_read_b64 v[44:45], v97 offset:64
	ds_read_b64 v[46:47], v97 offset:96
	ds_read_b64 v[52:53], v97 offset:2304
	ds_read_b64 v[54:55], v97 offset:2336
	ds_read_b64 v[48:49], v97 offset:2368
	ds_read_b64 v[50:51], v97 offset:2400
	ds_read_b64 v[64:65], v98 offset:8704
	ds_read_b64 v[66:67], v98 offset:8736
	ds_read_b64 v[68:69], v98 offset:11008
	ds_read_b64 v[70:71], v98 offset:11040
	ds_read_b64 v[76:77], v98 offset:8768
	ds_read_b64 v[78:79], v98 offset:8800
	ds_read_b64 v[112:113], v98 offset:11072
	ds_read_b64 v[114:115], v98 offset:11104
	s_waitcnt lgkmcnt(6)
	v_mfma_f32_16x16x32_bf16 v[72:75], v[64:67], v[56:59], 0
	v_mov_b32_e32 v0, s93
	s_waitcnt lgkmcnt(4)
	v_mfma_f32_16x16x32_bf16 v[68:71], v[68:71], v[52:55], 0
	s_waitcnt lgkmcnt(2)
	v_mfma_f32_16x16x32_bf16 v[72:75], v[76:79], v[44:47], v[72:75]
	s_waitcnt lgkmcnt(0)
	v_mfma_f32_16x16x32_bf16 v[68:71], v[112:115], v[48:51], v[68:71]
	v_mov_b32_e32 v112, s93
	s_nop 4
	v_cndmask_b32_e64 v0, v72, v0, s[8:9]
	v_cndmask_b32_e64 v0, v0, v72, s[10:11]
	v_mfma_f32_16x16x32_bf16 v[64:67], v[64:67], v[52:55], 0
	v_cndmask_b32_e64 v3, v74, 0, s[12:13]
	v_cndmask_b32_e64 v1, v68, v112, s[8:9]
	v_cndmask_b32_e64 v68, v1, v68, s[10:11]
	v_cndmask_b32_e64 v1, 0, v73, s[10:11]
	v_cndmask_b32_e64 v72, v75, 0, s[14:15]
	v_mfma_f32_16x16x32_bf16 v[64:67], v[76:79], v[48:51], v[64:67]
	v_cvt_pk_bf16_f32 v0, v0, v1
	v_cvt_pk_bf16_f32 v1, v3, v72
	ds_read_b128 v[72:75], v99 offset:35328
	ds_read_b128 v[76:79], v99 offset:35392
	v_cndmask_b32_e64 v69, 0, v69, s[10:11]
	v_cndmask_b32_e64 v70, v70, 0, s[12:13]
	v_cndmask_b32_e64 v71, v71, 0, s[14:15]
	v_mov_b32_e32 v3, v2
	v_cvt_pk_bf16_f32 v64, v64, v65
	v_cvt_pk_bf16_f32 v65, v66, v67
	v_cvt_pk_bf16_f32 v66, v68, v69
	v_cvt_pk_bf16_f32 v67, v70, v71
	v_mfma_f32_16x16x32_bf16 v[68:71], v[60:63], v[0:3], 0
	s_waitcnt lgkmcnt(1)
	v_pk_mul_f32 v[0:1], v[42:43], v[74:75]
	s_waitcnt lgkmcnt(0)
	v_pk_mul_f32 v[78:79], v[38:39], v[78:79]
	v_pk_mul_f32 v[74:75], v[36:37], v[76:77]
	v_pk_mul_f32 v[72:73], v[40:41], v[72:73]
	v_cvt_pk_bf16_f32 v74, v74, v75
	v_cvt_pk_bf16_f32 v75, v78, v79
	ds_read_b128 v[76:79], v99 offset:35456
	ds_read_b128 v[112:115], v99 offset:35520
	v_cvt_pk_bf16_f32 v72, v72, v73
	v_cvt_pk_bf16_f32 v73, v0, v1
	v_mfma_f32_16x16x32_bf16 v[64:67], v[60:63], v[64:67], 0
	s_waitcnt lgkmcnt(1)
	v_pk_mul_f32 v[0:1], v[30:31], v[78:79]
	s_waitcnt lgkmcnt(0)
	v_pk_mul_f32 v[114:115], v[34:35], v[114:115]
	v_pk_mul_f32 v[78:79], v[32:33], v[112:113]
	v_pk_mul_f32 v[76:77], v[28:29], v[76:77]
	v_cvt_pk_bf16_f32 v78, v78, v79
	v_cvt_pk_bf16_f32 v79, v114, v115
	ds_read_b128 v[112:115], v99 offset:34816
	ds_read_b64_tr_b16 v[118:119], v100 offset:19712
	ds_read_b64_tr_b16 v[116:117], v100 offset:17408
	ds_read_b64_tr_b16 v[120:121], v100 offset:17440
	v_cvt_pk_bf16_f32 v76, v76, v77
	s_waitcnt lgkmcnt(3)
	v_pk_mul_f32 v[42:43], v[42:43], v[114:115]
	v_pk_mul_f32 v[40:41], v[40:41], v[112:113]
	ds_read_b128 v[112:115], v99 offset:34880
	ds_read_b64_tr_b16 v[122:123], v100 offset:19744
	v_cvt_pk_bf16_f32 v77, v0, v1
	v_mfma_f32_16x16x32_bf16 v[56:59], v[72:75], v[56:59], v[68:71]
	v_xor_b32_e32 v1, 0xffffffef, v88
	s_waitcnt lgkmcnt(1)
	v_pk_mul_f32 v[38:39], v[38:39], v[114:115]
	v_pk_mul_f32 v[36:37], v[36:37], v[112:113]
	v_mfma_f32_16x16x32_bf16 v[40:43], v[116:119], v[60:63], v[40:43]
	ds_read_b128 v[112:115], v99 offset:34944
	ds_read_b64_tr_b16 v[116:117], v100 offset:17472
	ds_read_b64_tr_b16 v[118:119], v100 offset:19776
	v_add_u32_e32 v0, 16, v88
	v_cndmask_b32_e64 v3, v111, v88, s[4:5]
	v_mfma_f32_16x16x32_bf16 v[52:55], v[72:75], v[52:55], v[64:67]
	s_waitcnt lgkmcnt(2)
	v_pk_mul_f32 v[30:31], v[30:31], v[114:115]
	v_pk_mul_f32 v[28:29], v[28:29], v[112:113]
	v_add_u32_e32 v1, s74, v1
	v_mfma_f32_16x16x32_bf16 v[44:47], v[76:79], v[44:47], v[56:59]
	s_waitcnt lgkmcnt(0)
	v_mfma_f32_16x16x32_bf16 v[28:31], v[116:119], v[60:63], v[28:31]
	ds_read_b128 v[112:115], v99 offset:35008
	ds_read_b64_tr_b16 v[116:117], v100 offset:17504
	ds_read_b64_tr_b16 v[118:119], v100 offset:19808
	s_waitcnt lgkmcnt(2)
	v_pk_mul_f32 v[34:35], v[34:35], v[114:115]
	v_mfma_f32_16x16x32_bf16 v[48:51], v[76:79], v[48:51], v[52:55]
	v_mul_f32_e64 v32, v32, v112
	v_mul_f32_e64 v33, v33, v113
	s_nop 0
	v_cndmask_b32_e64 v52, v1, v0, s[4:5]
	v_cvt_pk_bf16_f32 v1, v46, v47
	v_add_u32_e32 v46, s73, v3
	v_ashrrev_i32_e32 v47, 31, v46
	v_lshlrev_b64 v[46:47], 11, v[46:47]
	v_cvt_pk_bf16_f32 v0, v44, v45
	v_lshl_add_u64 v[46:47], v[86:87], 0, v[46:47]
	v_mfma_f32_16x16x32_bf16 v[36:39], v[120:123], v[60:63], v[36:39]
	global_store_dwordx2 v[46:47], v[0:1], off
	v_add_u32_e32 v0, s73, v52
	v_ashrrev_i32_e32 v1, 31, v0
	s_waitcnt lgkmcnt(0)
	v_mfma_f32_16x16x32_bf16 v[32:35], v[116:119], v[60:63], v[32:35]
	v_lshlrev_b64 v[0:1], 11, v[0:1]
	v_cvt_pk_bf16_f32 v44, v48, v49
	v_cvt_pk_bf16_f32 v45, v50, v51
	v_lshl_add_u64 v[0:1], v[86:87], 0, v[0:1]
	global_store_dwordx2 v[0:1], v[44:45], off
	s_and_saveexec_b64 s[56:57], vcc
	s_cbranch_execz .LBB0_882
	s_waitcnt vmcnt(8)
	v_cvt_f32_f16_e32 v60, v20
	v_cvt_f32_f16_sdwa v59, v20 dst_sel:DWORD dst_unused:UNUSED_PAD src0_sel:WORD_1
	v_cvt_f32_f16_e32 v58, v21
	v_cvt_f32_f16_sdwa v57, v21 dst_sel:DWORD dst_unused:UNUSED_PAD src0_sel:WORD_1
	v_add_f32_dpp v0, v60, v60 row_shr:1 row_mask:0xf bank_mask:0xf bound_ctrl:1
	v_add_f32_dpp v1, v59, v59 row_shr:1 row_mask:0xf bank_mask:0xf bound_ctrl:1
	v_mov_b32_e32 v46, v2
	v_add_f32_dpp v0, v0, v0 row_shr:2 row_mask:0xf bank_mask:0xf bound_ctrl:1
	v_add_f32_dpp v1, v1, v1 row_shr:2 row_mask:0xf bank_mask:0xf bound_ctrl:1
	v_cvt_f32_f16_e32 v56, v22
	v_add_f32_dpp v0, v0, v0 row_shr:4 row_mask:0xf bank_mask:0xf bound_ctrl:1
	v_add_f32_dpp v20, v58, v58 row_shr:1 row_mask:0xf bank_mask:0xf bound_ctrl:1
	v_add_f32_dpp v1, v1, v1 row_shr:4 row_mask:0xf bank_mask:0xf bound_ctrl:1
	v_add_f32_dpp v0, v0, v0 row_shr:8 row_mask:0xf bank_mask:0xf bound_ctrl:1
	v_add_f32_dpp v20, v20, v20 row_shr:2 row_mask:0xf bank_mask:0xf bound_ctrl:1
	v_add_f32_dpp v1, v1, v1 row_shr:8 row_mask:0xf bank_mask:0xf bound_ctrl:1
	v_mov_b32_dpp v46, v0 row_bcast:15 row_mask:0xa bank_mask:0xf
	v_add_f32_e32 v62, v0, v46
	v_mov_b32_e32 v0, v2
	v_cvt_f32_f16_sdwa v55, v22 dst_sel:DWORD dst_unused:UNUSED_PAD src0_sel:WORD_1
	v_add_f32_dpp v21, v57, v57 row_shr:1 row_mask:0xf bank_mask:0xf bound_ctrl:1
	v_add_f32_dpp v20, v20, v20 row_shr:4 row_mask:0xf bank_mask:0xf bound_ctrl:1
	v_mov_b32_dpp v0, v1 row_bcast:15 row_mask:0xa bank_mask:0xf
	v_add_f32_dpp v21, v21, v21 row_shr:2 row_mask:0xf bank_mask:0xf bound_ctrl:1
	v_add_f32_dpp v20, v20, v20 row_shr:8 row_mask:0xf bank_mask:0xf bound_ctrl:1
	v_add_f32_e32 v63, v1, v0
	v_mov_b32_e32 v0, v2
	v_cvt_f32_f16_e32 v54, v23
	v_add_f32_dpp v22, v56, v56 row_shr:1 row_mask:0xf bank_mask:0xf bound_ctrl:1
	v_add_f32_dpp v21, v21, v21 row_shr:4 row_mask:0xf bank_mask:0xf bound_ctrl:1
	v_mov_b32_dpp v0, v20 row_bcast:15 row_mask:0xa bank_mask:0xf
	v_add_f32_dpp v22, v22, v22 row_shr:2 row_mask:0xf bank_mask:0xf bound_ctrl:1
	v_add_f32_dpp v21, v21, v21 row_shr:8 row_mask:0xf bank_mask:0xf bound_ctrl:1
	v_add_f32_e32 v64, v20, v0
	v_mov_b32_e32 v0, v2
	v_cvt_f32_f16_sdwa v3, v23 dst_sel:DWORD dst_unused:UNUSED_PAD src0_sel:WORD_1
	v_add_f32_dpp v23, v55, v55 row_shr:1 row_mask:0xf bank_mask:0xf bound_ctrl:1
	v_add_f32_dpp v22, v22, v22 row_shr:4 row_mask:0xf bank_mask:0xf bound_ctrl:1
	v_mov_b32_dpp v0, v21 row_bcast:15 row_mask:0xa bank_mask:0xf
	v_add_f32_dpp v23, v23, v23 row_shr:2 row_mask:0xf bank_mask:0xf bound_ctrl:1
	v_add_f32_dpp v22, v22, v22 row_shr:8 row_mask:0xf bank_mask:0xf bound_ctrl:1
	v_add_f32_e32 v65, v21, v0
	v_mov_b32_e32 v0, v2
	v_add_f32_dpp v44, v54, v54 row_shr:1 row_mask:0xf bank_mask:0xf bound_ctrl:1
	v_add_f32_dpp v23, v23, v23 row_shr:4 row_mask:0xf bank_mask:0xf bound_ctrl:1
	v_mov_b32_dpp v0, v22 row_bcast:15 row_mask:0xa bank_mask:0xf
	ds_bpermute_b32 v1, v91, v62
	v_add_f32_dpp v44, v44, v44 row_shr:2 row_mask:0xf bank_mask:0xf bound_ctrl:1
	v_add_f32_dpp v23, v23, v23 row_shr:8 row_mask:0xf bank_mask:0xf bound_ctrl:1
	v_add_f32_e32 v61, v22, v0
	v_mov_b32_e32 v0, v2
	v_add_f32_dpp v44, v44, v44 row_shr:4 row_mask:0xf bank_mask:0xf bound_ctrl:1
	v_add_f32_dpp v45, v3, v3 row_shr:1 row_mask:0xf bank_mask:0xf bound_ctrl:1
	v_mov_b32_dpp v0, v23 row_bcast:15 row_mask:0xa bank_mask:0xf
	v_add_f32_dpp v44, v44, v44 row_shr:8 row_mask:0xf bank_mask:0xf bound_ctrl:1
	v_add_f32_e32 v66, v23, v0
	v_mov_b32_e32 v0, v2
	v_add_f32_dpp v45, v45, v45 row_shr:2 row_mask:0xf bank_mask:0xf bound_ctrl:1
	ds_bpermute_b32 v22, v91, v64
	v_mov_b32_dpp v0, v44 row_bcast:15 row_mask:0xa bank_mask:0xf
	v_add_f32_e32 v67, v44, v0
	s_waitcnt lgkmcnt(1)
	v_sub_f32_e32 v0, v62, v1
	ds_bpermute_b32 v1, v91, v63
	v_med3_f32 v0, v0, s69, v189
	v_add_f32_dpp v45, v45, v45 row_shr:4 row_mask:0xf bank_mask:0xf bound_ctrl:1
	v_mul_f32_e32 v0, 0x3fb8aa3b, v0
	v_exp_f32_e32 v20, v0
	v_add_f32_dpp v45, v45, v45 row_shr:8 row_mask:0xf bank_mask:0xf bound_ctrl:1
	v_mov_b32_e32 v0, v2
	s_waitcnt lgkmcnt(0)
	v_sub_f32_e32 v1, v63, v1
	v_med3_f32 v1, v1, s69, v189
	v_mov_b32_dpp v0, v45 row_bcast:15 row_mask:0xa bank_mask:0xf
	v_add_f32_e32 v68, v45, v0
	v_mul_f32_e32 v1, 0x3fb8aa3b, v1
	v_exp_f32_e32 v21, v1
	ds_bpermute_b32 v1, v91, v65
	ds_bpermute_b32 v46, v91, v61
	ds_bpermute_b32 v47, v91, v66
	ds_bpermute_b32 v48, v91, v67
	ds_bpermute_b32 v49, v91, v68
	v_sub_f32_e32 v22, v64, v22
	s_waitcnt lgkmcnt(4)
	v_sub_f32_e32 v1, v65, v1
	s_waitcnt lgkmcnt(3)
	v_sub_f32_e32 v46, v61, v46
	s_waitcnt lgkmcnt(2)
	v_sub_f32_e32 v47, v66, v47
	s_waitcnt lgkmcnt(1)
	v_sub_f32_e32 v48, v67, v48
	s_waitcnt lgkmcnt(0)
	v_sub_f32_e32 v49, v68, v49
	v_med3_f32 v22, v22, s69, v189
	v_med3_f32 v1, v1, s69, v189
	v_med3_f32 v46, v46, s69, v189
	v_med3_f32 v47, v47, s69, v189
	v_med3_f32 v48, v48, s69, v189
	v_med3_f32 v49, v49, s69, v189
	v_mul_f32_e32 v22, 0x3fb8aa3b, v22
	v_mul_f32_e32 v1, 0x3fb8aa3b, v1
	v_mul_f32_e32 v46, 0x3fb8aa3b, v46
	v_mul_f32_e32 v47, 0x3fb8aa3b, v47
	v_mul_f32_e32 v48, 0x3fb8aa3b, v48
	v_mul_f32_e32 v49, 0x3fb8aa3b, v49
	v_exp_f32_e32 v44, v22
	v_exp_f32_e32 v45, v1
	v_exp_f32_e32 v46, v46
	v_exp_f32_e32 v47, v47
	v_exp_f32_e32 v48, v48
	v_exp_f32_e32 v49, v49
	ds_bpermute_b32 v0, v92, v20
	ds_bpermute_b32 v1, v92, v21
	ds_bpermute_b32 v22, v92, v44
	ds_bpermute_b32 v23, v92, v45
	ds_bpermute_b32 v52, v92, v46
	ds_bpermute_b32 v53, v92, v47
	ds_bpermute_b32 v50, v92, v48
	ds_bpermute_b32 v51, v92, v49
	s_and_saveexec_b64 s[16:17], s[6:7]
	s_cbranch_execz .LBB0_881
	v_mul_f32_e32 v62, 0x3fb8aa3b, v62
	v_mul_f32_e32 v63, 0x3fb8aa3b, v63
	v_mul_f32_e32 v64, 0x3fb8aa3b, v64
	v_mul_f32_e32 v65, 0x3fb8aa3b, v65
	v_exp_f32_e32 v62, v62
	v_exp_f32_e32 v63, v63
	v_exp_f32_e32 v64, v64
	v_exp_f32_e32 v65, v65
	v_mul_f32_e32 v61, 0x3fb8aa3b, v61
	ds_write_b128 v101, v[62:65]
	v_exp_f32_e32 v62, v61
	v_mul_f32_e32 v61, 0x3fb8aa3b, v66
	v_exp_f32_e32 v63, v61
	v_mul_f32_e32 v61, 0x3fb8aa3b, v67
	v_exp_f32_e32 v64, v61
	v_mul_f32_e32 v61, 0x3fb8aa3b, v68
	v_exp_f32_e32 v65, v61
	ds_write_b128 v101, v[62:65] offset:16
	s_branch .LBB0_881

.LBB0_1370:
	s_add_i32 s1, s57, -1
	s_waitcnt vmcnt(7)
	ds_write_b128 v175, v[72:75]
	ds_write_b128 v175, v[68:71] offset:8704
	ds_write_b128 v175, v[64:67] offset:17408
	v_cndmask_b32_e32 v65, v180, v173, vcc
	v_xor_b32_e32 v66, 0xffffffef, v173
	v_xor_b32_e32 v70, 0xffffffcf, v173
	s_min_u32 s18, s1, s0
	v_add_u32_e32 v69, 48, v173
	v_xor_b32_e32 v67, 0xffffffdf, v173
	v_add_u32_e32 v71, s55, v66
	v_add_u32_e32 v66, s56, v65
	v_add_u32_e32 v70, s55, v70
	v_lshl_add_u32 v73, s18, 5, v174
	v_add_u32_e32 v64, 16, v173
	v_add_u32_e32 v68, 32, v173
	v_add_u32_e32 v65, s55, v67
	v_ashrrev_i32_e32 v67, 31, v66
	v_cndmask_b32_e32 v69, v70, v69, vcc
	v_xad_u32 v70, v73, -1, s55
	v_cndmask_b32_e32 v71, v71, v64, vcc
	v_cndmask_b32_e32 v68, v65, v68, vcc
	v_lshlrev_b64 v[64:65], 11, v[66:67]
	v_cndmask_b32_e32 v67, v70, v73, vcc
	s_min_u32 s42, s57, s0
	v_lshl_add_u64 v[242:243], v[170:171], 0, v[64:65]
	v_add_u32_e32 v64, s56, v67
	v_lshl_add_u32 v72, s42, 5, v174
	v_ashrrev_i32_e32 v65, 31, v64
	v_cvt_pk_bf16_f32 v60, v44, v45
	v_cvt_pk_bf16_f32 v61, v46, v47
	v_cvt_pk_bf16_f32 v62, v40, v41
	v_cvt_pk_bf16_f32 v63, v42, v43
	v_xad_u32 v74, v72, -1, s55
	v_lshlrev_b64 v[64:65], 13, v[64:65]
	v_cndmask_b32_e32 v66, v74, v72, vcc
	v_or_b32_e32 v64, v64, v181
	v_add_u32_e32 v238, s56, v68
	v_add_u32_e32 v240, s56, v69
	v_add_u32_e32 v244, s56, v66
	v_lshl_add_u64 v[66:67], s[36:37], 0, v[64:65]
	v_lshl_add_u64 v[68:69], s[38:39], 0, v[64:65]
	v_lshl_add_u64 v[64:65], s[40:41], 0, v[64:65]
	v_add_u32_e32 v236, s56, v71
	global_load_dwordx4 v[72:75], v[66:67], off
	s_nop 0
	global_load_dwordx4 v[68:71], v[68:69], off
	s_nop 0
	global_load_dwordx4 v[64:67], v[64:65], off
	s_waitcnt lgkmcnt(0)
	s_barrier
	ds_read_b64 v[188:189], v178
	ds_read_b64 v[190:191], v178 offset:32
	ds_read_b64 v[192:193], v178 offset:4352
	ds_read_b64 v[194:195], v178 offset:4384
	ds_read_b64 v[196:197], v178 offset:4416
	ds_read_b64 v[198:199], v178 offset:4448
	ds_read_b64 v[200:201], v179 offset:8704
	ds_read_b64 v[202:203], v179 offset:8736
	ds_read_b64 v[204:205], v179 offset:13056
	ds_read_b64 v[206:207], v179 offset:13088
	ds_read_b64_tr_b16 v[210:211], v176 offset:13056
	ds_read_b64_tr_b16 v[212:213], v177 offset:17408
	ds_read_b64_tr_b16 v[214:215], v177 offset:21760
	ds_read_b64_tr_b16 v[208:209], v176 offset:8704
	ds_read_b64_tr_b16 v[216:217], v176 offset:8736
	ds_read_b64_tr_b16 v[220:221], v176 offset:8768
	ds_read_b64_tr_b16 v[222:223], v176 offset:13120
	ds_read_b64_tr_b16 v[218:219], v176 offset:13088
	ds_read_b64_tr_b16 v[230:231], v176 offset:8928
	s_waitcnt lgkmcnt(7)
	v_lshlrev_b32_e32 v232, 16, v212
	v_and_b32_e32 v233, 0xffff0000, v212
	v_lshlrev_b32_e32 v234, 16, v213
	v_and_b32_e32 v235, 0xffff0000, v213
	s_waitcnt lgkmcnt(6)
	v_lshlrev_b32_e32 v246, 16, v214
	v_and_b32_e32 v247, 0xffff0000, v214
	v_lshlrev_b32_e32 v248, 16, v215
	v_and_b32_e32 v249, 0xffff0000, v215
	v_mov_b32_e32 v159, v158
	v_mfma_f32_16x16x32_bf16 v[226:229], v[60:63], v[192:195], 0
	v_mul_f32_e64 v232, v150, v232
	v_mul_f32_e64 v233, v151, v233
	v_pk_mul_f32 v[234:235], v[152:153], v[234:235]
	v_pk_mul_f32 v[44:45], v[164:165], v[44:45]
	v_mfma_f32_16x16x32_bf16 v[60:63], v[60:63], v[188:191], 0
	v_mul_f32_e64 v46, v158, v46
	v_mul_f32_e64 v47, v159, v47
	v_pk_mul_f32 v[40:41], v[164:165], v[40:41]
	v_pk_mul_f32 v[42:43], v[158:159], v[42:43]
	v_mfma_f32_16x16x32_bf16 v[188:191], v[200:203], v[188:191], 0
	v_cvt_pk_bf16_f32 v52, v36, v37
	v_cvt_pk_bf16_f32 v53, v38, v39
	v_cvt_pk_bf16_f32 v54, v32, v33
	v_mfma_f32_16x16x32_bf16 v[200:203], v[200:203], v[192:195], 0
	v_cvt_pk_bf16_f32 v55, v34, v35
	v_cvt_pk_bf16_f32 v56, v28, v29
	v_cvt_pk_bf16_f32 v57, v30, v31
	v_mfma_f32_16x16x32_bf16 v[192:195], v[204:207], v[192:195], 0
	v_mul_f32_e64 v206, v154, v246
	v_mul_f32_e64 v207, v155, v247
	v_pk_mul_f32 v[246:247], v[156:157], v[248:249]
	v_cvt_pk_bf16_f32 v204, v232, v233
	v_cvt_pk_bf16_f32 v205, v234, v235
	v_cvt_pk_bf16_f32 v206, v206, v207
	v_cvt_pk_bf16_f32 v207, v246, v247
	v_pk_mul_f32 v[36:37], v[164:165], v[36:37]
	v_pk_mul_f32 v[32:33], v[164:165], v[32:33]
	s_waitcnt lgkmcnt(5)
	v_mfma_f32_16x16x32_bf16 v[44:47], v[208:211], v[204:207], v[44:47]
	ds_read_b64_tr_b16 v[210:211], v176 offset:13152
	ds_read_b64_tr_b16 v[208:209], v176 offset:8800
	ds_read_b64_tr_b16 v[232:233], v176 offset:8832
	v_pk_mul_f32 v[28:29], v[164:165], v[28:29]
	v_pk_mul_f32 v[38:39], v[158:159], v[38:39]
	s_waitcnt lgkmcnt(4)
	v_mfma_f32_16x16x32_bf16 v[40:43], v[216:219], v[204:207], v[40:43]
	ds_read_b64_tr_b16 v[216:217], v176 offset:8864
	ds_read_b64_tr_b16 v[234:235], v176 offset:13184
	ds_read_b64_tr_b16 v[218:219], v176 offset:13216
	v_pk_mul_f32 v[34:35], v[158:159], v[34:35]
	v_pk_mul_f32 v[30:31], v[158:159], v[30:31]
	v_mfma_f32_16x16x32_bf16 v[36:39], v[220:223], v[204:207], v[36:39]
	v_ashrrev_i32_e32 v245, 31, v244
	v_ashrrev_i32_e32 v237, 31, v236
	v_cvt_pk_bf16_f32 v58, v24, v25
	s_waitcnt lgkmcnt(4)
	v_mfma_f32_16x16x32_bf16 v[32:35], v[208:211], v[204:207], v[32:35]
	ds_read_b64_tr_b16 v[208:209], v176 offset:8896
	ds_read_b64_tr_b16 v[210:211], v176 offset:13248
	v_cvt_pk_bf16_f32 v59, v26, v27
	s_waitcnt lgkmcnt(3)
	v_mfma_f32_16x16x32_bf16 v[220:223], v[232:235], v[204:207], v[28:31]
	ds_read_b64_tr_b16 v[232:233], v176 offset:13280
	v_cvt_pk_bf16_f32 v48, v20, v21
	v_cvt_pk_bf16_f32 v49, v22, v23
	v_lshlrev_b64 v[28:29], 13, v[244:245]
	v_cvt_pk_bf16_f32 v50, v16, v17
	v_cvt_pk_bf16_f32 v51, v18, v19
	v_pk_mul_f32 v[24:25], v[164:165], v[24:25]
	v_pk_mul_f32 v[20:21], v[164:165], v[20:21]
	v_pk_mul_f32 v[16:17], v[164:165], v[16:17]
	v_pk_mul_f32 v[26:27], v[158:159], v[26:27]
	v_pk_mul_f32 v[22:23], v[158:159], v[22:23]
	v_pk_mul_f32 v[18:19], v[158:159], v[18:19]
	v_ashrrev_i32_e32 v239, 31, v238
	v_ashrrev_i32_e32 v241, 31, v240
	v_lshlrev_b64 v[236:237], 11, v[236:237]
	v_or_b32_e32 v28, v28, v181
	v_lshlrev_b64 v[246:247], 11, v[238:239]
	v_lshlrev_b64 v[248:249], 11, v[240:241]
	s_waitcnt lgkmcnt(3)
	v_mfma_f32_16x16x32_bf16 v[216:219], v[216:219], v[204:207], v[24:27]
	v_lshl_add_u64 v[234:235], v[170:171], 0, v[236:237]
	v_lshl_add_u64 v[236:237], s[36:37], 0, v[28:29]
	v_lshl_add_u64 v[238:239], s[38:39], 0, v[28:29]
	s_waitcnt lgkmcnt(1)
	v_mfma_f32_16x16x32_bf16 v[208:211], v[208:211], v[204:207], v[20:23]
	ds_read_b64 v[24:25], v179 offset:8768
	ds_read_b64 v[26:27], v179 offset:8800
	v_lshl_add_u64 v[240:241], s[40:41], 0, v[28:29]
	ds_read_b64 v[28:29], v179 offset:13120
	ds_read_b64 v[30:31], v179 offset:13152
	s_waitcnt lgkmcnt(4)
	v_mfma_f32_16x16x32_bf16 v[204:207], v[230:233], v[204:207], v[16:19]
	v_mov_b32_e32 v3, v2
	ds_read_b64 v[16:17], v178 offset:64
	ds_read_b64 v[18:19], v178 offset:96
	v_mfma_f32_16x16x32_bf16 v[226:229], v[52:55], v[196:199], v[226:229]
	v_add_u32_e32 v186, 0x9800, v179
	s_add_i32 s57, s57, 2
	s_waitcnt lgkmcnt(0)
	v_mfma_f32_16x16x32_bf16 v[20:23], v[52:55], v[16:19], v[60:63]
	ds_read_b64 v[52:53], v178 offset:4480
	ds_read_b64 v[54:55], v178 offset:4512
	s_nop 1
	ds_read_b64 v[60:61], v178 offset:128
	ds_read_b64 v[62:63], v178 offset:160
	v_add_u32_e32 v173, 64, v173
	v_subrev_u32_e32 v180, 64, v180
	v_mfma_f32_16x16x32_bf16 v[16:19], v[24:27], v[16:19], v[188:191]
	s_cmp_ge_u32 s1, s58
	v_mfma_f32_16x16x32_bf16 v[24:27], v[24:27], v[196:199], v[200:203]
	v_mfma_f32_16x16x32_bf16 v[28:31], v[28:31], v[196:199], v[192:195]
	s_nop 2
	ds_read_b64 v[192:193], v179 offset:8832
	ds_read_b64 v[194:195], v179 offset:8864
	ds_read_b64 v[196:197], v178 offset:192
	ds_read_b64 v[198:199], v178 offset:224
	ds_read_b64 v[200:201], v178 offset:4544
	ds_read_b64 v[202:203], v178 offset:4576
	s_waitcnt lgkmcnt(8)
	v_mfma_f32_16x16x32_bf16 v[188:191], v[56:59], v[52:55], v[226:229]
	s_waitcnt lgkmcnt(6)
	v_mfma_f32_16x16x32_bf16 v[20:23], v[56:59], v[60:63], v[20:23]
	ds_read_b64 v[56:57], v179 offset:13184
	ds_read_b64 v[58:59], v179 offset:13216
	ds_read_b64 v[226:227], v179 offset:8896
	ds_read_b64 v[228:229], v179 offset:8928
	ds_read_b64 v[230:231], v179 offset:13248
	ds_read_b64 v[232:233], v179 offset:13280
	s_waitcnt vmcnt(5)
	ds_write_b128 v175, v[12:15] offset:26112
	ds_write_b128 v175, v[8:11] offset:34816
	ds_write_b128 v175, v[4:7] offset:43520
	s_waitcnt lgkmcnt(13)
	v_mfma_f32_16x16x32_bf16 v[16:19], v[192:195], v[60:63], v[16:19]
	v_mfma_f32_16x16x32_bf16 v[4:7], v[192:195], v[52:55], v[24:27]
	s_waitcnt lgkmcnt(7)
	v_mfma_f32_16x16x32_bf16 v[8:11], v[56:59], v[52:55], v[28:31]
	s_nop 0
	v_cvt_pk_bf16_f32 v24, v44, v45
	v_cvt_pk_bf16_f32 v25, v46, v47
	v_cvt_pk_bf16_f32 v26, v40, v41
	s_waitcnt lgkmcnt(5)
	v_mfma_f32_16x16x32_bf16 v[16:19], v[226:229], v[196:199], v[16:19]
	v_mul_f32_e64 v28, v164, v44
	v_mul_f32_e64 v29, v165, v45
	v_cvt_pk_bf16_f32 v27, v42, v43
	v_pk_mul_f32 v[30:31], v[158:159], v[46:47]
	v_mfma_f32_16x16x32_bf16 v[4:7], v[226:229], v[200:203], v[4:7]
	v_cvt_pk_bf16_f32 v52, v36, v37
	s_nop 1
	v_pk_mul_f32 v[18:19], v[146:147], v[18:19]
	v_pk_mul_f32 v[0:1], v[142:143], v[16:17]
	s_waitcnt lgkmcnt(3)
	v_mfma_f32_16x16x32_bf16 v[8:11], v[230:233], v[200:203], v[8:11]
	v_cvt_pk_bf16_f32 v0, v0, v1
	v_pk_mul_f32 v[6:7], v[148:149], v[6:7]
	v_pk_mul_f32 v[4:5], v[144:145], v[4:5]
	v_cvt_pk_bf16_f32 v1, v18, v19
	v_cvt_pk_bf16_f32 v4, v4, v5
	s_nop 2
	v_pk_mul_f32 v[16:17], v[146:147], v[10:11]
	v_pk_mul_f32 v[44:45], v[142:143], v[8:9]
	v_cvt_pk_bf16_f32 v5, v6, v7
	v_cvt_pk_bf16_f32 v6, v44, v45
	v_cvt_pk_bf16_f32 v7, v16, v17
	v_mfma_f32_16x16x32_bf16 v[12:15], v[48:51], v[200:203], v[188:191]
	v_cvt_pk_bf16_f32 v53, v38, v39
	v_pk_mul_f32 v[38:39], v[158:159], v[38:39]
	v_pk_mul_f32 v[36:37], v[164:165], v[36:37]
	v_mfma_f32_16x16x32_bf16 v[20:23], v[48:51], v[196:199], v[20:23]
	v_cvt_pk_bf16_f32 v54, v32, v33
	v_cvt_pk_bf16_f32 v55, v34, v35
	v_pk_mul_f32 v[42:43], v[158:159], v[42:43]
	v_mfma_f32_16x16x32_bf16 v[8:11], v[212:215], v[0:3], 0
	v_mul_f32_e64 v40, v164, v40
	v_mul_f32_e64 v41, v165, v41
	v_pk_mul_f32 v[34:35], v[158:159], v[34:35]
	v_pk_mul_f32 v[32:33], v[164:165], v[32:33]
	v_mfma_f32_16x16x32_bf16 v[4:7], v[212:215], v[4:7], 0
	v_mul_f32_e64 v50, v158, v222
	v_mul_f32_e64 v51, v159, v223
	s_nop 0
	v_pk_fma_f32 v[8:9], v[162:163], v[20:21], v[8:9]
	v_pk_mul_f32 v[48:49], v[164:165], v[220:221]
	v_cvt_pk_bf16_f32 v8, v8, v9
	v_cvt_pk_bf16_f32 v56, v220, v221
	s_nop 0
	v_pk_fma_f32 v[0:1], v[166:167], v[14:15], v[6:7]
	v_pk_fma_f32 v[6:7], v[168:169], v[22:23], v[10:11]
	v_pk_fma_f32 v[4:5], v[160:161], v[12:13], v[4:5]
	v_cvt_pk_bf16_f32 v9, v6, v7
	v_cvt_pk_bf16_f32 v4, v4, v5
	v_cvt_pk_bf16_f32 v5, v0, v1
	global_store_dwordx2 v[242:243], v[8:9], off
	global_store_dwordx2 v[234:235], v[4:5], off
	global_load_dwordx4 v[12:15], v[236:237], off
	s_nop 0
	global_load_dwordx4 v[8:11], v[238:239], off
	global_load_dwordx4 v[4:7], v[240:241], off
	s_waitcnt lgkmcnt(0)
	s_barrier
	ds_read_b64 v[16:17], v178 offset:26112
	ds_read_b64 v[18:19], v178 offset:26144
	ds_read_b64 v[20:21], v178 offset:30464
	ds_read_b64 v[22:23], v178 offset:30496
	ds_read_b64 v[60:61], v178 offset:30528
	ds_read_b64 v[62:63], v178 offset:30560
	ds_read_b64 v[44:45], v179 offset:34816
	ds_read_b64 v[46:47], v179 offset:34848
	ds_read_b64 v[188:189], v186 offset:256
	ds_read_b64 v[190:191], v186 offset:288
	ds_read_b64_tr_b16 v[194:195], v176 offset:39168
	ds_read_b64_tr_b16 v[196:197], v177 offset:43520
	ds_read_b64_tr_b16 v[198:199], v177 offset:47872
	ds_read_b64_tr_b16 v[192:193], v176 offset:34816
	ds_read_b64_tr_b16 v[200:201], v176 offset:34848
	ds_read_b64_tr_b16 v[212:213], v176 offset:34880
	ds_read_b64_tr_b16 v[214:215], v176 offset:39232
	s_waitcnt lgkmcnt(13)
	v_mfma_f32_16x16x32_bf16 v[226:229], v[24:27], v[20:23], 0
	s_waitcnt lgkmcnt(5)
	v_lshlrev_b32_e32 v0, 16, v196
	v_and_b32_e32 v1, 0xffff0000, v196
	v_pk_mul_f32 v[0:1], v[150:151], v[0:1]
	v_mfma_f32_16x16x32_bf16 v[234:237], v[24:27], v[16:19], 0
	v_lshlrev_b32_e32 v24, 16, v197
	v_and_b32_e32 v25, 0xffff0000, v197
	v_pk_mul_f32 v[24:25], v[152:153], v[24:25]
	v_mfma_f32_16x16x32_bf16 v[238:241], v[44:47], v[16:19], 0
	s_waitcnt lgkmcnt(4)
	v_lshlrev_b32_e32 v16, 16, v198
	v_and_b32_e32 v17, 0xffff0000, v198
	v_lshlrev_b32_e32 v18, 16, v199
	v_and_b32_e32 v19, 0xffff0000, v199
	v_mfma_f32_16x16x32_bf16 v[242:245], v[44:47], v[20:23], 0
	ds_read_b64_tr_b16 v[202:203], v176 offset:39200
	ds_read_b64_tr_b16 v[230:231], v176 offset:35040
	v_cvt_pk_bf16_f32 v57, v222, v223
	v_cvt_pk_bf16_f32 v58, v216, v217
	v_mfma_f32_16x16x32_bf16 v[188:191], v[188:191], v[20:23], 0
	v_mul_f32_e64 v20, v154, v16
	v_mul_f32_e64 v21, v155, v17
	v_pk_mul_f32 v[22:23], v[156:157], v[18:19]
	v_cvt_pk_bf16_f32 v16, v0, v1
	v_cvt_pk_bf16_f32 v17, v24, v25
	v_cvt_pk_bf16_f32 v18, v20, v21
	v_cvt_pk_bf16_f32 v19, v22, v23
	ds_read_b64_tr_b16 v[22:23], v176 offset:39264
	ds_read_b64_tr_b16 v[20:21], v176 offset:34912
	ds_read_b64_tr_b16 v[24:25], v176 offset:34944
	s_waitcnt lgkmcnt(8)
	v_mfma_f32_16x16x32_bf16 v[44:47], v[192:195], v[16:19], v[28:31]
	ds_read_b64_tr_b16 v[192:193], v176 offset:34976
	ds_read_b64_tr_b16 v[26:27], v176 offset:39296
	ds_read_b64_tr_b16 v[194:195], v176 offset:39328
	ds_read_b64_tr_b16 v[232:233], v176 offset:39392
	v_cvt_pk_bf16_f32 v59, v218, v219
	s_waitcnt lgkmcnt(9)
	v_mfma_f32_16x16x32_bf16 v[36:39], v[212:215], v[16:19], v[36:39]
	ds_read_b64_tr_b16 v[212:213], v176 offset:35008
	ds_read_b64_tr_b16 v[214:215], v176 offset:39360
	s_waitcnt lgkmcnt(10)
	v_mfma_f32_16x16x32_bf16 v[40:43], v[200:203], v[16:19], v[40:43]
	v_mul_f32_e64 v202, v158, v218
	v_mul_f32_e64 v203, v159, v219
	v_pk_mul_f32 v[200:201], v[164:165], v[216:217]
	ds_read_b64 v[216:217], v178 offset:26240
	ds_read_b64 v[218:219], v178 offset:26272
	s_waitcnt lgkmcnt(9)
	v_mfma_f32_16x16x32_bf16 v[32:35], v[20:23], v[16:19], v[32:35]
	v_mul_f32_e64 v22, v158, v210
	v_mul_f32_e64 v23, v159, v211
	v_pk_mul_f32 v[20:21], v[164:165], v[208:209]
	s_waitcnt lgkmcnt(6)
	v_mfma_f32_16x16x32_bf16 v[28:31], v[24:27], v[16:19], v[48:51]
	s_waitcnt lgkmcnt(5)
	v_mfma_f32_16x16x32_bf16 v[24:27], v[192:195], v[16:19], v[200:203]
	ds_read_b64 v[192:193], v179 offset:34880
	ds_read_b64 v[194:195], v179 offset:34912
	v_pk_mul_f32 v[50:51], v[158:159], v[206:207]
	v_pk_mul_f32 v[48:49], v[164:165], v[204:205]
	s_waitcnt lgkmcnt(4)
	v_mfma_f32_16x16x32_bf16 v[20:23], v[212:215], v[16:19], v[20:23]
	ds_read_b64 v[212:213], v186 offset:320
	ds_read_b64 v[214:215], v186 offset:352
	v_cvt_pk_bf16_f32 v202, v204, v205
	v_cvt_pk_bf16_f32 v203, v206, v207
	v_mfma_f32_16x16x32_bf16 v[16:19], v[230:233], v[16:19], v[48:51]
	ds_read_b64 v[204:205], v178 offset:26304
	ds_read_b64 v[206:207], v178 offset:26336
	v_cvt_pk_bf16_f32 v200, v208, v209
	v_cvt_pk_bf16_f32 v201, v210, v211
	ds_read_b64 v[48:49], v178 offset:26176
	ds_read_b64 v[50:51], v178 offset:26208
	v_mfma_f32_16x16x32_bf16 v[226:229], v[52:55], v[60:63], v[226:229]
	s_waitcnt lgkmcnt(0)
	v_mfma_f32_16x16x32_bf16 v[52:55], v[52:55], v[48:51], v[234:237]
	v_mfma_f32_16x16x32_bf16 v[48:51], v[192:195], v[48:51], v[238:241]
	v_mfma_f32_16x16x32_bf16 v[192:195], v[192:195], v[60:63], v[242:245]
	v_mfma_f32_16x16x32_bf16 v[60:63], v[212:215], v[60:63], v[188:191]
	s_nop 2
	ds_read_b64 v[188:189], v178 offset:30592
	ds_read_b64 v[190:191], v178 offset:30624
	s_waitcnt lgkmcnt(0)
	v_mfma_f32_16x16x32_bf16 v[212:215], v[56:59], v[188:191], v[226:229]
	v_mfma_f32_16x16x32_bf16 v[52:55], v[56:59], v[216:219], v[52:55]
	ds_read_b64 v[56:57], v179 offset:34944
	ds_read_b64 v[58:59], v179 offset:34976
	s_waitcnt lgkmcnt(0)
	v_mfma_f32_16x16x32_bf16 v[48:51], v[56:59], v[216:219], v[48:51]
	v_mfma_f32_16x16x32_bf16 v[56:59], v[56:59], v[188:191], v[192:195]
	s_nop 2
	ds_read_b64 v[192:193], v186 offset:384
	ds_read_b64 v[194:195], v186 offset:416
	s_waitcnt lgkmcnt(0)
	v_mfma_f32_16x16x32_bf16 v[60:63], v[192:195], v[188:191], v[60:63]
	ds_read_b64 v[188:189], v178 offset:30656
	ds_read_b64 v[190:191], v178 offset:30688
	ds_read_b64 v[182:183], v179 offset:35008
	ds_read_b64 v[184:185], v179 offset:35040
	s_waitcnt lgkmcnt(0)
	v_mfma_f32_16x16x32_bf16 v[48:51], v[182:185], v[204:207], v[48:51]
	s_nop 7
	v_pk_mul_f32 v[50:51], v[146:147], v[50:51]
	v_mfma_f32_16x16x32_bf16 v[56:59], v[182:185], v[188:191], v[56:59]
	ds_read_b64 v[182:183], v186 offset:448
	ds_read_b64 v[184:185], v186 offset:480
	v_pk_mul_f32 v[0:1], v[142:143], v[48:49]
	s_waitcnt lgkmcnt(0)
	v_mfma_f32_16x16x32_bf16 v[60:63], v[182:185], v[188:191], v[60:63]
	s_nop 3
	v_mul_f32_e64 v182, v148, v58
	v_mul_f32_e64 v183, v149, v59
	v_pk_mul_f32 v[48:49], v[144:145], v[56:57]
	v_cvt_pk_bf16_f32 v0, v0, v1
	v_pk_mul_f32 v[62:63], v[146:147], v[62:63]
	v_pk_mul_f32 v[60:61], v[142:143], v[60:61]
	v_cvt_pk_bf16_f32 v1, v50, v51
	v_cvt_pk_bf16_f32 v48, v48, v49
	v_cvt_pk_bf16_f32 v49, v182, v183
	v_cvt_pk_bf16_f32 v50, v60, v61
	v_cvt_pk_bf16_f32 v51, v62, v63
	v_mfma_f32_16x16x32_bf16 v[192:195], v[200:203], v[188:191], v[212:215]
	v_mfma_f32_16x16x32_bf16 v[52:55], v[200:203], v[204:207], v[52:55]
	v_lshl_add_u64 v[200:201], v[170:171], 0, v[246:247]
	v_lshl_add_u64 v[202:203], v[170:171], 0, v[248:249]
	v_mfma_f32_16x16x32_bf16 v[56:59], v[196:199], v[0:3], 0
	v_mfma_f32_16x16x32_bf16 v[48:51], v[196:199], v[48:51], 0
	s_nop 6
	v_fma_f32 v52, v162, v52, v56
	v_fma_f32 v53, v163, v53, v57
	v_pk_fma_f32 v[0:1], v[166:167], v[194:195], v[50:51]
	v_pk_fma_f32 v[50:51], v[168:169], v[54:55], v[58:59]
	v_pk_fma_f32 v[48:49], v[160:161], v[192:193], v[48:49]
	v_cvt_pk_bf16_f32 v52, v52, v53
	v_cvt_pk_bf16_f32 v53, v50, v51
	v_cvt_pk_bf16_f32 v48, v48, v49
	v_cvt_pk_bf16_f32 v49, v0, v1
	global_store_dwordx2 v[200:201], v[52:53], off
	global_store_dwordx2 v[202:203], v[48:49], off
	s_cbranch_scc0 .LBB0_1370
	s_andn2_b64 vcc, exec, s[6:7]
	s_cbranch_vccnz .LBB0_1354
	s_add_u32 s0, s28, s14
	s_addc_u32 s1, s29, s15
	v_lshl_add_u64 v[0:1], v[112:113], 2, s[0:1]
	s_waitcnt vmcnt(2)
	v_lshl_add_u64 v[4:5], v[0:1], 0, v[76:77]
	global_store_dword v[4:5], v44, off nt
	v_lshl_add_u64 v[4:5], v[0:1], 0, v[78:79]
	global_store_dword v[4:5], v45, off nt
	v_lshl_add_u64 v[4:5], v[0:1], 0, v[80:81]
	global_store_dword v[4:5], v46, off nt
	v_lshl_add_u64 v[4:5], v[0:1], 0, v[82:83]
	global_store_dword v[4:5], v47, off nt
	v_lshl_add_u64 v[4:5], v[0:1], 0, v[84:85]
	global_store_dword v[4:5], v40, off nt
	v_lshl_add_u64 v[4:5], v[0:1], 0, v[86:87]
	global_store_dword v[4:5], v41, off nt
	v_lshl_add_u64 v[4:5], v[0:1], 0, v[88:89]
	global_store_dword v[4:5], v42, off nt
	v_lshl_add_u64 v[4:5], v[0:1], 0, v[90:91]
	global_store_dword v[4:5], v43, off nt
	v_lshl_add_u64 v[4:5], v[0:1], 0, v[92:93]
	global_store_dword v[4:5], v36, off nt
	v_lshl_add_u64 v[4:5], v[0:1], 0, v[94:95]
	global_store_dword v[4:5], v37, off nt
	v_lshl_add_u64 v[4:5], v[0:1], 0, v[96:97]
	global_store_dword v[4:5], v38, off nt
	v_lshl_add_u64 v[4:5], v[0:1], 0, v[98:99]
	global_store_dword v[4:5], v39, off nt
	v_lshl_add_u64 v[4:5], v[0:1], 0, v[100:101]
	global_store_dword v[4:5], v32, off nt
	v_lshl_add_u64 v[4:5], v[0:1], 0, v[102:103]
	global_store_dword v[4:5], v33, off nt
	v_lshl_add_u64 v[4:5], v[0:1], 0, v[104:105]
	global_store_dword v[4:5], v34, off nt
	v_lshl_add_u64 v[4:5], v[0:1], 0, v[106:107]
	global_store_dword v[4:5], v35, off nt
	v_lshl_add_u64 v[4:5], v[0:1], 0, v[108:109]
	global_store_dword v[4:5], v28, off nt
	v_lshl_add_u64 v[4:5], v[0:1], 0, v[110:111]
	global_store_dword v[4:5], v29, off nt
	v_lshl_add_u64 v[4:5], v[0:1], 0, v[138:139]
	global_store_dword v[4:5], v30, off nt
	v_lshl_add_u64 v[4:5], v[0:1], 0, v[136:137]
	global_store_dword v[4:5], v31, off nt
	v_lshl_add_u64 v[4:5], v[0:1], 0, v[134:135]
	global_store_dword v[4:5], v24, off nt
	v_lshl_add_u64 v[4:5], v[0:1], 0, v[132:133]
	global_store_dword v[4:5], v25, off nt
	v_lshl_add_u64 v[4:5], v[0:1], 0, v[130:131]
	global_store_dword v[4:5], v26, off nt
	v_lshl_add_u64 v[4:5], v[0:1], 0, v[128:129]
	global_store_dword v[4:5], v27, off nt
	v_lshl_add_u64 v[4:5], v[0:1], 0, v[126:127]
	global_store_dword v[4:5], v20, off nt
	v_lshl_add_u64 v[4:5], v[0:1], 0, v[124:125]
	global_store_dword v[4:5], v21, off nt
	v_lshl_add_u64 v[4:5], v[0:1], 0, v[122:123]
	global_store_dword v[4:5], v22, off nt
	v_lshl_add_u64 v[4:5], v[0:1], 0, v[120:121]
	global_store_dword v[4:5], v23, off nt
	v_lshl_add_u64 v[4:5], v[0:1], 0, v[118:119]
	global_store_dword v[4:5], v16, off nt
	v_lshl_add_u64 v[4:5], v[0:1], 0, v[116:117]
	global_store_dword v[4:5], v17, off nt
	v_lshl_add_u64 v[4:5], v[0:1], 0, v[114:115]
	v_lshl_add_u64 v[0:1], v[0:1], 0, v[140:141]
	global_store_dword v[4:5], v18, off nt
	global_store_dword v[0:1], v19, off nt
	s_branch .LBB0_1354
